# MLP1 GEMMs: epilogue ss/shw loads requested at top of the tile's last K-iteration (latency under MFMAs)
# speedup vs baseline: 1.0006x; 1.0005x over previous
.LBB0_130:
	s_add_u32 s8, s60, 0xfffc0080
	s_addc_u32 s9, s61, -1
	s_add_i32 s16, 0, 0x10000
	v_add_u32_e32 v150, s16, v168
	ds_read_b128 v[128:131], v150
	ds_read_b128 v[132:135], v150 offset:1024
	ds_read_b128 v[146:149], v150 offset:2048
	ds_read_b128 v[150:153], v150 offset:3072
	s_cmp_eq_u32 s15, 12
	s_cselect_b32 s9, s5, s9
	s_cselect_b32 s8, s10, s8
	s_cselect_b32 s63, s1, s14
	s_cselect_b32 s62, s12, s13
	s_cbranch_scc0 .Lpf130_skip
	v_readlane_b32 s22, v250, 14
	v_readlane_b32 s23, v250, 15
	v_readlane_b32 s24, v250, 16
	v_readlane_b32 s25, v250, 17
	v_lshl_add_u32 v246, s65, 8, v159
	v_lshl_or_b32 v247, s66, 8, v169
	s_ashr_i32 s26, s65, 5
	s_lshl_b32 s26, s26, 14
	v_lshlrev_b32_e32 v246, 3, v246
	v_lshlrev_b32_e32 v247, 2, v247
	s_add_u32 s24, s24, s26
	s_addc_u32 s25, s25, 0
	global_load_dwordx2 v[242:243], v246, s[22:23]
	global_load_dwordx2 v[244:245], v246, s[22:23] offset:128
	global_load_dwordx2 v[220:221], v246, s[22:23] offset:256
	global_load_dwordx2 v[222:223], v246, s[22:23] offset:384
	global_load_dwordx2 v[224:225], v246, s[22:23] offset:1024
	global_load_dwordx2 v[226:227], v246, s[22:23] offset:1152
	global_load_dwordx2 v[228:229], v246, s[22:23] offset:1280
	global_load_dwordx2 v[230:231], v246, s[22:23] offset:1408
	global_load_dwordx4 v[232:235], v247, s[24:25] offset:16
	global_load_dwordx4 v[236:239], v247, s[24:25]
.Lpf130_skip:
	v_lshl_add_u64 v[164:165], s[60:61], 0, v[142:143]
	s_add_i32 m0, s38, 0xc000
	ds_read_b128 v[154:157], v170
	ds_read_b128 v[172:175], v170 offset:1024
	ds_read_b128 v[176:179], v170 offset:2048
	ds_read_b128 v[180:183], v170 offset:3072
	ds_read_b128 v[184:187], v170 offset:4096
	ds_read_b128 v[188:191], v170 offset:5120
	ds_read_b128 v[192:195], v170 offset:6144
	ds_read_b128 v[196:199], v170 offset:7168
	global_load_lds_dwordx4 v[164:165], off
	v_lshl_add_u64 v[164:165], s[60:61], 0, v[144:145]
	s_add_i32 m0, s38, 0xe000
	s_nop 0
	global_load_lds_dwordx4 v[164:165], off
	s_waitcnt lgkmcnt(8)
	s_barrier
	s_waitcnt lgkmcnt(0)
	s_setprio 1
	s_waitcnt lgkmcnt(0)
	v_mfma_f32_16x16x32_bf16 v[124:127], v[128:131], v[154:157], v[124:127]
	v_mfma_f32_16x16x32_bf16 v[120:123], v[146:149], v[154:157], v[120:123]
	v_mfma_f32_16x16x32_bf16 v[116:119], v[128:131], v[176:179], v[116:119]
	v_mfma_f32_16x16x32_bf16 v[112:115], v[146:149], v[176:179], v[112:115]
	v_mfma_f32_16x16x32_bf16 v[108:111], v[128:131], v[184:187], v[108:111]
	v_mfma_f32_16x16x32_bf16 v[104:107], v[146:149], v[184:187], v[104:107]
	v_mfma_f32_16x16x32_bf16 v[100:103], v[128:131], v[192:195], v[100:103]
	v_mfma_f32_16x16x32_bf16 v[96:99], v[146:149], v[192:195], v[96:99]
	v_mfma_f32_16x16x32_bf16 v[124:127], v[132:135], v[172:175], v[124:127]
	v_mfma_f32_16x16x32_bf16 v[120:123], v[150:153], v[172:175], v[120:123]
	v_mfma_f32_16x16x32_bf16 v[116:119], v[132:135], v[180:183], v[116:119]
	v_mfma_f32_16x16x32_bf16 v[112:115], v[150:153], v[180:183], v[112:115]
	v_mfma_f32_16x16x32_bf16 v[108:111], v[132:135], v[188:191], v[108:111]
	v_mfma_f32_16x16x32_bf16 v[104:107], v[150:153], v[188:191], v[104:107]
	v_mfma_f32_16x16x32_bf16 v[100:103], v[132:135], v[196:199], v[100:103]
	v_mfma_f32_16x16x32_bf16 v[96:99], v[150:153], v[196:199], v[96:99]
	s_setprio 0
	s_barrier
	s_add_i32 s18, 0, 0x14000
	s_add_i32 s16, s16, s37
	v_add_u32_e32 v158, s18, v168
	v_lshl_add_u64 v[164:165], s[62:63], 0, v[160:161]
	s_mov_b32 m0, s16
	ds_read_b128 v[200:203], v158
	ds_read_b128 v[204:207], v158 offset:1024
	ds_read_b128 v[208:211], v158 offset:2048
	ds_read_b128 v[212:215], v158 offset:3072
	global_load_lds_dwordx4 v[164:165], off
	v_lshl_add_u64 v[166:167], s[62:63], 0, v[136:137]
	s_add_i32 m0, s16, 0x2000
	s_nop 0
	global_load_lds_dwordx4 v[166:167], off
	s_barrier
	s_waitcnt lgkmcnt(0)
	s_setprio 1
	s_waitcnt lgkmcnt(0)
	v_mfma_f32_16x16x32_bf16 v[68:71], v[200:203], v[154:157], v[68:71]
	v_mfma_f32_16x16x32_bf16 v[64:67], v[208:211], v[154:157], v[64:67]
	v_mfma_f32_16x16x32_bf16 v[52:55], v[200:203], v[176:179], v[52:55]
	v_mfma_f32_16x16x32_bf16 v[48:51], v[208:211], v[176:179], v[48:51]
	v_mfma_f32_16x16x32_bf16 v[44:47], v[200:203], v[184:187], v[44:47]
	v_mfma_f32_16x16x32_bf16 v[40:43], v[208:211], v[184:187], v[40:43]
	v_mfma_f32_16x16x32_bf16 v[36:39], v[200:203], v[192:195], v[36:39]
	v_mfma_f32_16x16x32_bf16 v[32:35], v[208:211], v[192:195], v[32:35]
	v_mfma_f32_16x16x32_bf16 v[68:71], v[204:207], v[172:175], v[68:71]
	v_mfma_f32_16x16x32_bf16 v[64:67], v[212:215], v[172:175], v[64:67]
	v_mfma_f32_16x16x32_bf16 v[52:55], v[204:207], v[180:183], v[52:55]
	v_mfma_f32_16x16x32_bf16 v[48:51], v[212:215], v[180:183], v[48:51]
	v_mfma_f32_16x16x32_bf16 v[44:47], v[204:207], v[188:191], v[44:47]
	v_mfma_f32_16x16x32_bf16 v[40:43], v[212:215], v[188:191], v[40:43]
	v_mfma_f32_16x16x32_bf16 v[36:39], v[204:207], v[196:199], v[36:39]
	v_mfma_f32_16x16x32_bf16 v[32:35], v[212:215], v[196:199], v[32:35]
	s_setprio 0
	s_mov_b32 m0, s38
	v_lshl_add_u64 v[216:217], s[8:9], 0, v[140:141]
	s_barrier
	ds_read_b128 v[154:157], v170 offset:16384
	ds_read_b128 v[172:175], v170 offset:17408
	ds_read_b128 v[176:179], v170 offset:18432
	ds_read_b128 v[180:183], v170 offset:19456
	ds_read_b128 v[184:187], v170 offset:20480
	ds_read_b128 v[188:191], v170 offset:21504
	ds_read_b128 v[192:195], v170 offset:22528
	ds_read_b128 v[196:199], v170 offset:23552
	global_load_lds_dwordx4 v[216:217], off
	v_lshl_add_u64 v[218:219], s[8:9], 0, v[138:139]
	s_mov_b32 m0, s39
	s_nop 0
	global_load_lds_dwordx4 v[218:219], off
	s_barrier
	s_waitcnt lgkmcnt(0)
	s_setprio 1
	s_waitcnt lgkmcnt(0)
	v_mfma_f32_16x16x32_bf16 v[92:95], v[128:131], v[154:157], v[92:95]
	v_mfma_f32_16x16x32_bf16 v[88:91], v[146:149], v[154:157], v[88:91]
	v_mfma_f32_16x16x32_bf16 v[84:87], v[128:131], v[176:179], v[84:87]
	v_mfma_f32_16x16x32_bf16 v[80:83], v[146:149], v[176:179], v[80:83]
	v_mfma_f32_16x16x32_bf16 v[76:79], v[128:131], v[184:187], v[76:79]
	v_mfma_f32_16x16x32_bf16 v[72:75], v[146:149], v[184:187], v[72:75]
	v_mfma_f32_16x16x32_bf16 v[60:63], v[128:131], v[192:195], v[60:63]
	v_mfma_f32_16x16x32_bf16 v[56:59], v[146:149], v[192:195], v[56:59]
	v_mfma_f32_16x16x32_bf16 v[92:95], v[132:135], v[172:175], v[92:95]
	v_mfma_f32_16x16x32_bf16 v[88:91], v[150:153], v[172:175], v[88:91]
	v_mfma_f32_16x16x32_bf16 v[84:87], v[132:135], v[180:183], v[84:87]
	v_mfma_f32_16x16x32_bf16 v[80:83], v[150:153], v[180:183], v[80:83]
	v_mfma_f32_16x16x32_bf16 v[76:79], v[132:135], v[188:191], v[76:79]
	v_mfma_f32_16x16x32_bf16 v[72:75], v[150:153], v[188:191], v[72:75]
	v_mfma_f32_16x16x32_bf16 v[60:63], v[132:135], v[196:199], v[60:63]
	v_mfma_f32_16x16x32_bf16 v[56:59], v[150:153], v[196:199], v[56:59]
	s_setprio 0
	s_barrier
	s_add_u32 s16, s62, 0x40000
	s_addc_u32 s17, s63, 0
	s_add_i32 s18, s18, s37
	v_lshl_add_u64 v[128:129], s[16:17], 0, v[160:161]
	s_mov_b32 m0, s18
	s_nop 0
	global_load_lds_dwordx4 v[128:129], off
	v_lshl_add_u64 v[128:129], s[16:17], 0, v[136:137]
	s_add_i32 m0, s18, 0x2000
	s_nop 0
	global_load_lds_dwordx4 v[128:129], off
	s_waitcnt vmcnt(6)
	s_barrier
	s_setprio 1
	v_mfma_f32_16x16x32_bf16 v[28:31], v[200:203], v[154:157], v[28:31]
	v_mfma_f32_16x16x32_bf16 v[24:27], v[208:211], v[154:157], v[24:27]
	v_mfma_f32_16x16x32_bf16 v[20:23], v[200:203], v[176:179], v[20:23]
	v_mfma_f32_16x16x32_bf16 v[16:19], v[208:211], v[176:179], v[16:19]
	v_mfma_f32_16x16x32_bf16 v[12:15], v[200:203], v[184:187], v[12:15]
	v_mfma_f32_16x16x32_bf16 v[8:11], v[208:211], v[184:187], v[8:11]
	v_mfma_f32_16x16x32_bf16 v[4:7], v[200:203], v[192:195], v[4:7]
	v_mfma_f32_16x16x32_bf16 v[0:3], v[208:211], v[192:195], v[0:3]
	v_mfma_f32_16x16x32_bf16 v[28:31], v[204:207], v[172:175], v[28:31]
	v_mfma_f32_16x16x32_bf16 v[24:27], v[212:215], v[172:175], v[24:27]
	v_mfma_f32_16x16x32_bf16 v[20:23], v[204:207], v[180:183], v[20:23]
	v_mfma_f32_16x16x32_bf16 v[16:19], v[212:215], v[180:183], v[16:19]
	v_mfma_f32_16x16x32_bf16 v[12:15], v[204:207], v[188:191], v[12:15]
	v_mfma_f32_16x16x32_bf16 v[8:11], v[212:215], v[188:191], v[8:11]
	v_mfma_f32_16x16x32_bf16 v[4:7], v[204:207], v[196:199], v[4:7]
	v_mfma_f32_16x16x32_bf16 v[0:3], v[212:215], v[196:199], v[0:3]
	s_setprio 0
	s_add_i32 s16, 0, 0x18000
	v_add_u32_e32 v150, s16, v168
	s_barrier
	ds_read_b128 v[128:131], v150
	ds_read_b128 v[132:135], v150 offset:1024
	ds_read_b128 v[146:149], v150 offset:2048
	ds_read_b128 v[150:153], v150 offset:3072
	s_add_u32 s8, s8, 0x40000
	s_addc_u32 s9, s9, 0
	s_mov_b32 m0, s40
	v_lshl_add_u64 v[200:201], s[8:9], 0, v[140:141]
	ds_read_b128 v[154:157], v170 offset:32768
	ds_read_b128 v[172:175], v170 offset:33792
	ds_read_b128 v[176:179], v170 offset:34816
	ds_read_b128 v[180:183], v170 offset:35840
	ds_read_b128 v[184:187], v170 offset:36864
	ds_read_b128 v[188:191], v170 offset:37888
	ds_read_b128 v[192:195], v170 offset:38912
	ds_read_b128 v[196:199], v170 offset:39936
	global_load_lds_dwordx4 v[200:201], off
	v_lshl_add_u64 v[200:201], s[8:9], 0, v[138:139]
	s_mov_b32 m0, s41
	s_nop 0
	global_load_lds_dwordx4 v[200:201], off
	s_waitcnt lgkmcnt(8)
	s_barrier
	s_waitcnt lgkmcnt(0)
	s_setprio 1
	s_waitcnt lgkmcnt(0)
	v_mfma_f32_16x16x32_bf16 v[124:127], v[128:131], v[154:157], v[124:127]
	v_mfma_f32_16x16x32_bf16 v[120:123], v[146:149], v[154:157], v[120:123]
	v_mfma_f32_16x16x32_bf16 v[116:119], v[128:131], v[176:179], v[116:119]
	v_mfma_f32_16x16x32_bf16 v[112:115], v[146:149], v[176:179], v[112:115]
	v_mfma_f32_16x16x32_bf16 v[108:111], v[128:131], v[184:187], v[108:111]
	v_mfma_f32_16x16x32_bf16 v[104:107], v[146:149], v[184:187], v[104:107]
	v_mfma_f32_16x16x32_bf16 v[100:103], v[128:131], v[192:195], v[100:103]
	v_mfma_f32_16x16x32_bf16 v[96:99], v[146:149], v[192:195], v[96:99]
	v_mfma_f32_16x16x32_bf16 v[124:127], v[132:135], v[172:175], v[124:127]
	v_mfma_f32_16x16x32_bf16 v[120:123], v[150:153], v[172:175], v[120:123]
	v_mfma_f32_16x16x32_bf16 v[116:119], v[132:135], v[180:183], v[116:119]
	v_mfma_f32_16x16x32_bf16 v[112:115], v[150:153], v[180:183], v[112:115]
	v_mfma_f32_16x16x32_bf16 v[108:111], v[132:135], v[188:191], v[108:111]
	v_mfma_f32_16x16x32_bf16 v[104:107], v[150:153], v[188:191], v[104:107]
	v_mfma_f32_16x16x32_bf16 v[100:103], v[132:135], v[196:199], v[100:103]
	v_mfma_f32_16x16x32_bf16 v[96:99], v[150:153], v[196:199], v[96:99]
	s_setprio 0
	s_barrier
	s_add_i32 s17, 0, 0x1c000
	s_add_i32 s8, s16, s37
	v_add_u32_e32 v158, s17, v168
	v_lshl_add_u64 v[164:165], v[164:165], 0, s[74:75]
	s_mov_b32 m0, s8
	ds_read_b128 v[200:203], v158
	ds_read_b128 v[204:207], v158 offset:1024
	ds_read_b128 v[208:211], v158 offset:2048
	ds_read_b128 v[212:215], v158 offset:3072
	global_load_lds_dwordx4 v[164:165], off
	v_lshl_add_u64 v[164:165], v[166:167], 0, s[74:75]
	s_add_i32 m0, s8, 0x2000
	s_nop 0
	global_load_lds_dwordx4 v[164:165], off
	s_barrier
	s_waitcnt lgkmcnt(0)
	s_setprio 1
	s_waitcnt lgkmcnt(0)
	v_mfma_f32_16x16x32_bf16 v[68:71], v[200:203], v[154:157], v[68:71]
	v_mfma_f32_16x16x32_bf16 v[64:67], v[208:211], v[154:157], v[64:67]
	v_mfma_f32_16x16x32_bf16 v[52:55], v[200:203], v[176:179], v[52:55]
	v_mfma_f32_16x16x32_bf16 v[48:51], v[208:211], v[176:179], v[48:51]
	v_mfma_f32_16x16x32_bf16 v[44:47], v[200:203], v[184:187], v[44:47]
	v_mfma_f32_16x16x32_bf16 v[40:43], v[208:211], v[184:187], v[40:43]
	v_mfma_f32_16x16x32_bf16 v[36:39], v[200:203], v[192:195], v[36:39]
	v_mfma_f32_16x16x32_bf16 v[32:35], v[208:211], v[192:195], v[32:35]
	v_mfma_f32_16x16x32_bf16 v[68:71], v[204:207], v[172:175], v[68:71]
	v_mfma_f32_16x16x32_bf16 v[64:67], v[212:215], v[172:175], v[64:67]
	v_mfma_f32_16x16x32_bf16 v[52:55], v[204:207], v[180:183], v[52:55]
	v_mfma_f32_16x16x32_bf16 v[48:51], v[212:215], v[180:183], v[48:51]
	v_mfma_f32_16x16x32_bf16 v[44:47], v[204:207], v[188:191], v[44:47]
	v_mfma_f32_16x16x32_bf16 v[40:43], v[212:215], v[188:191], v[40:43]
	v_mfma_f32_16x16x32_bf16 v[36:39], v[204:207], v[196:199], v[36:39]
	v_mfma_f32_16x16x32_bf16 v[32:35], v[212:215], v[196:199], v[32:35]
	s_setprio 0
	s_mov_b32 m0, s42
	v_lshl_add_u64 v[164:165], v[216:217], 0, s[74:75]
	s_barrier
	ds_read_b128 v[154:157], v170 offset:49152
	ds_read_b128 v[172:175], v170 offset:50176
	ds_read_b128 v[176:179], v170 offset:51200
	ds_read_b128 v[180:183], v170 offset:52224
	ds_read_b128 v[184:187], v170 offset:53248
	ds_read_b128 v[188:191], v170 offset:54272
	ds_read_b128 v[192:195], v170 offset:55296
	ds_read_b128 v[196:199], v170 offset:56320
	global_load_lds_dwordx4 v[164:165], off
	v_lshl_add_u64 v[164:165], v[218:219], 0, s[74:75]
	s_mov_b32 m0, s43
	s_nop 0
	global_load_lds_dwordx4 v[164:165], off
	s_barrier
	s_waitcnt lgkmcnt(0)
	s_setprio 1
	s_waitcnt lgkmcnt(0)
	v_mfma_f32_16x16x32_bf16 v[92:95], v[128:131], v[154:157], v[92:95]
	v_mfma_f32_16x16x32_bf16 v[88:91], v[146:149], v[154:157], v[88:91]
	v_mfma_f32_16x16x32_bf16 v[84:87], v[128:131], v[176:179], v[84:87]
	v_mfma_f32_16x16x32_bf16 v[80:83], v[146:149], v[176:179], v[80:83]
	v_mfma_f32_16x16x32_bf16 v[76:79], v[128:131], v[184:187], v[76:79]
	v_mfma_f32_16x16x32_bf16 v[72:75], v[146:149], v[184:187], v[72:75]
	v_mfma_f32_16x16x32_bf16 v[60:63], v[128:131], v[192:195], v[60:63]
	v_mfma_f32_16x16x32_bf16 v[56:59], v[146:149], v[192:195], v[56:59]
	v_mfma_f32_16x16x32_bf16 v[92:95], v[132:135], v[172:175], v[92:95]
	v_mfma_f32_16x16x32_bf16 v[88:91], v[150:153], v[172:175], v[88:91]
	v_mfma_f32_16x16x32_bf16 v[84:87], v[132:135], v[180:183], v[84:87]
	v_mfma_f32_16x16x32_bf16 v[80:83], v[150:153], v[180:183], v[80:83]
	v_mfma_f32_16x16x32_bf16 v[76:79], v[132:135], v[188:191], v[76:79]
	v_mfma_f32_16x16x32_bf16 v[72:75], v[150:153], v[188:191], v[72:75]
	v_mfma_f32_16x16x32_bf16 v[60:63], v[132:135], v[196:199], v[60:63]
	v_mfma_f32_16x16x32_bf16 v[56:59], v[150:153], v[196:199], v[56:59]
	s_setprio 0
	s_barrier
	s_add_u32 s8, s62, 0x40080
	s_addc_u32 s9, s63, 0
	s_add_i32 s16, s17, s37
	v_lshl_add_u64 v[128:129], s[8:9], 0, v[160:161]
	s_mov_b32 m0, s16
	s_nop 0
	global_load_lds_dwordx4 v[128:129], off
	v_lshl_add_u64 v[128:129], s[8:9], 0, v[136:137]
	s_add_i32 m0, s16, 0x2000
	s_nop 0
	global_load_lds_dwordx4 v[128:129], off
	s_waitcnt vmcnt(6)
	s_barrier
	s_setprio 1
	v_mfma_f32_16x16x32_bf16 v[28:31], v[200:203], v[154:157], v[28:31]
	v_mfma_f32_16x16x32_bf16 v[24:27], v[208:211], v[154:157], v[24:27]
	v_mfma_f32_16x16x32_bf16 v[20:23], v[200:203], v[176:179], v[20:23]
	v_mfma_f32_16x16x32_bf16 v[16:19], v[208:211], v[176:179], v[16:19]
	v_mfma_f32_16x16x32_bf16 v[12:15], v[200:203], v[184:187], v[12:15]
	v_mfma_f32_16x16x32_bf16 v[8:11], v[208:211], v[184:187], v[8:11]
	v_mfma_f32_16x16x32_bf16 v[4:7], v[200:203], v[192:195], v[4:7]
	v_mfma_f32_16x16x32_bf16 v[0:3], v[208:211], v[192:195], v[0:3]
	v_mfma_f32_16x16x32_bf16 v[28:31], v[204:207], v[172:175], v[28:31]
	v_mfma_f32_16x16x32_bf16 v[24:27], v[212:215], v[172:175], v[24:27]
	v_mfma_f32_16x16x32_bf16 v[20:23], v[204:207], v[180:183], v[20:23]
	v_mfma_f32_16x16x32_bf16 v[16:19], v[212:215], v[180:183], v[16:19]
	v_mfma_f32_16x16x32_bf16 v[12:15], v[204:207], v[188:191], v[12:15]
	v_mfma_f32_16x16x32_bf16 v[8:11], v[212:215], v[188:191], v[8:11]
	v_mfma_f32_16x16x32_bf16 v[4:7], v[204:207], v[196:199], v[4:7]
	v_mfma_f32_16x16x32_bf16 v[0:3], v[212:215], v[196:199], v[0:3]
	s_setprio 0
	s_add_i32 s15, s15, 2
	s_add_u32 s60, s60, 0x100
	s_addc_u32 s61, s61, 0
	s_add_u32 s13, s13, 0x100
	s_addc_u32 s14, s14, 0
	s_cmp_gt_u32 s15, 13
	s_barrier
	s_cbranch_scc0 .LBB0_130
	v_lshl_add_u32 v146, s65, 8, v159
	v_readlane_b32 s8, v250, 14
	v_ashrrev_i32_e32 v147, 31, v146
	v_readlane_b32 s9, v250, 15
	v_readlane_b32 s1, v250, 16
	v_lshl_or_b32 v156, s66, 8, v169
	v_lshl_add_u64 v[128:129], v[146:147], 3, s[8:9]
	s_ashr_i32 s8, s65, 5
	s_ashr_i32 s9, s8, 31
	s_lshl_b64 s[8:9], s[8:9], 14
	s_add_u32 s8, s1, s8
	v_readlane_b32 s1, v250, 17
	v_ashrrev_i32_e32 v157, 31, v156
	s_addc_u32 s9, s1, s9
	v_lshl_add_u64 v[164:165], v[156:157], 2, s[8:9]
	v_readlane_b32 s8, v253, 29
	v_readlane_b32 s9, v253, 30
	s_mov_b32 s1, 0x100000
	s_mov_b32 s66, s0
	s_mov_b32 s65, s4
	s_mov_b64 s[20:21], s[6:7]
	v_readlane_b32 s62, v255, 4
	v_readlane_b32 s63, v255, 5
	s_waitcnt vmcnt(0)
	v_mov_b32_e32 v130, v242
	v_mov_b32_e32 v131, v243
	v_mov_b32_e32 v218, v244
	v_mov_b32_e32 v219, v245
	v_ffbh_u32_e32 v132, v131
	v_min_u32_e32 v132, 32, v132
	v_lshlrev_b64 v[130:131], v132, v[130:131]
	v_min_u32_e32 v130, 1, v130
	v_or_b32_e32 v130, v131, v130
	v_cvt_f32_u32_e32 v130, v130
	v_sub_u32_e32 v131, 32, v132
	v_ldexp_f32 v130, v130, v131
	v_mul_f32_e32 v130, 0x37800000, v130
	v_fmamk_f32 v158, v130, 0x3a800000, v240
	v_mov_b32_e32 v130, v218
	v_mov_b32_e32 v131, v219
	v_cmp_gt_f32_e32 vcc, s53, v158
	v_mul_f32_e32 v162, 0x4b800000, v158
	v_ffbh_u32_e32 v132, v131
	v_min_u32_e32 v132, 32, v132
	v_lshlrev_b64 v[130:131], v132, v[130:131]
	v_min_u32_e32 v130, 1, v130
	v_or_b32_e32 v130, v131, v130
	v_cvt_f32_u32_e32 v130, v130
	v_sub_u32_e32 v131, 32, v132
	v_cndmask_b32_e32 v158, v158, v162, vcc
	v_rsq_f32_e32 v158, v158
	v_ldexp_f32 v130, v130, v131
	v_mul_f32_e32 v130, 0x37800000, v130
	v_fmamk_f32 v171, v130, 0x3a800000, v240
	v_mov_b32_e32 v130, v220
	v_mov_b32_e32 v131, v221
	v_mul_f32_e32 v162, 0x45800000, v158
	v_cndmask_b32_e32 v184, v158, v162, vcc
	v_cmp_gt_f32_e32 vcc, s53, v171
	v_mul_f32_e32 v158, 0x4b800000, v171
	v_ffbh_u32_e32 v132, v131
	v_min_u32_e32 v132, 32, v132
	v_lshlrev_b64 v[130:131], v132, v[130:131]
	v_min_u32_e32 v130, 1, v130
	v_or_b32_e32 v130, v131, v130
	v_cvt_f32_u32_e32 v130, v130
	v_sub_u32_e32 v131, 32, v132
	v_cndmask_b32_e32 v158, v171, v158, vcc
	v_rsq_f32_e32 v158, v158
	v_ldexp_f32 v130, v130, v131
	v_mul_f32_e32 v130, 0x37800000, v130
	v_fmamk_f32 v172, v130, 0x3a800000, v240
	v_mov_b32_e32 v130, v222
	v_mov_b32_e32 v131, v223
	v_mul_f32_e32 v162, 0x45800000, v158
	v_cndmask_b32_e32 v182, v158, v162, vcc
	v_cmp_gt_f32_e32 vcc, s53, v172
	v_mul_f32_e32 v158, 0x4b800000, v172
	v_ffbh_u32_e32 v132, v131
	v_min_u32_e32 v132, 32, v132
	v_lshlrev_b64 v[130:131], v132, v[130:131]
	v_min_u32_e32 v130, 1, v130
	v_or_b32_e32 v130, v131, v130
	v_cvt_f32_u32_e32 v130, v130
	v_sub_u32_e32 v131, 32, v132
	v_cndmask_b32_e32 v158, v172, v158, vcc
	v_rsq_f32_e32 v158, v158
	v_ldexp_f32 v130, v130, v131
	v_mul_f32_e32 v130, 0x37800000, v130
	v_fmamk_f32 v173, v130, 0x3a800000, v240
	v_mov_b32_e32 v130, v224
	v_mov_b32_e32 v131, v225
	v_mul_f32_e32 v162, 0x45800000, v158
	v_cndmask_b32_e32 v180, v158, v162, vcc
	v_cmp_gt_f32_e32 vcc, s53, v173
	v_mul_f32_e32 v158, 0x4b800000, v173
	v_ffbh_u32_e32 v132, v131
	v_min_u32_e32 v132, 32, v132
	v_lshlrev_b64 v[130:131], v132, v[130:131]
	v_min_u32_e32 v130, 1, v130
	v_or_b32_e32 v130, v131, v130
	v_cvt_f32_u32_e32 v130, v130
	v_sub_u32_e32 v131, 32, v132
	v_cndmask_b32_e32 v158, v173, v158, vcc
	v_rsq_f32_e32 v158, v158
	v_ldexp_f32 v130, v130, v131
	v_mul_f32_e32 v130, 0x37800000, v130
	v_fmamk_f32 v174, v130, 0x3a800000, v240
	v_mov_b32_e32 v130, v226
	v_mov_b32_e32 v131, v227
	v_mul_f32_e32 v162, 0x45800000, v158
	v_cndmask_b32_e32 v178, v158, v162, vcc
	v_cmp_gt_f32_e32 vcc, s53, v174
	v_mul_f32_e32 v158, 0x4b800000, v174
	v_ffbh_u32_e32 v132, v131
	v_min_u32_e32 v132, 32, v132
	v_lshlrev_b64 v[130:131], v132, v[130:131]
	v_min_u32_e32 v130, 1, v130
	v_or_b32_e32 v130, v131, v130
	v_cvt_f32_u32_e32 v130, v130
	v_sub_u32_e32 v131, 32, v132
	v_cndmask_b32_e32 v158, v174, v158, vcc
	v_rsq_f32_e32 v158, v158
	v_ldexp_f32 v130, v130, v131
	v_mul_f32_e32 v130, 0x37800000, v130
	v_fmamk_f32 v175, v130, 0x3a800000, v240
	v_mov_b32_e32 v130, v228
	v_mov_b32_e32 v131, v229
	v_mul_f32_e32 v162, 0x45800000, v158
	v_mov_b32_e32 v128, v230
	v_mov_b32_e32 v129, v231
	v_cndmask_b32_e32 v176, v158, v162, vcc
	v_cmp_gt_f32_e32 vcc, s53, v175
	v_mul_f32_e32 v158, 0x4b800000, v175
	v_ffbh_u32_e32 v132, v131
	v_min_u32_e32 v132, 32, v132
	v_lshlrev_b64 v[130:131], v132, v[130:131]
	v_min_u32_e32 v130, 1, v130
	v_or_b32_e32 v130, v131, v130
	v_cvt_f32_u32_e32 v130, v130
	v_sub_u32_e32 v131, 32, v132
	v_cndmask_b32_e32 v158, v175, v158, vcc
	v_rsq_f32_e32 v158, v158
	v_ldexp_f32 v130, v130, v131
	v_mul_f32_e32 v130, 0x37800000, v130
	v_fmamk_f32 v177, v130, 0x3a800000, v240
	v_ffbh_u32_e32 v130, v129
	v_min_u32_e32 v130, 32, v130
	v_lshlrev_b64 v[128:129], v130, v[128:129]
	v_min_u32_e32 v128, 1, v128
	v_or_b32_e32 v128, v129, v128
	v_cvt_f32_u32_e32 v128, v128
	v_sub_u32_e32 v129, 32, v130
	v_mul_f32_e32 v162, 0x45800000, v158
	v_cndmask_b32_e32 v174, v158, v162, vcc
	v_ldexp_f32 v128, v128, v129
	v_mul_f32_e32 v128, 0x37800000, v128
	v_fmamk_f32 v179, v128, 0x3a800000, v240
	v_mov_b32_e32 v128, v232
	v_mov_b32_e32 v129, v233
	v_mov_b32_e32 v130, v234
	v_mov_b32_e32 v131, v235
	v_mov_b32_e32 v132, v236
	v_mov_b32_e32 v133, v237
	v_mov_b32_e32 v134, v238
	v_mov_b32_e32 v135, v239
	v_cmp_gt_f32_e32 vcc, s53, v177
	v_mul_f32_e32 v158, 0x4b800000, v177
	s_waitcnt vmcnt(0)
	v_pk_add_f32 v[148:149], v[130:131], 0 op_sel_hi:[1,0]
	v_pk_add_f32 v[152:153], v[134:135], 0 op_sel_hi:[1,0]
	v_pk_add_f32 v[154:155], v[132:133], 0 op_sel_hi:[1,0]
	v_pk_add_f32 v[150:151], v[128:129], 0 op_sel_hi:[1,0]
	global_load_dwordx4 v[128:131], v[164:165], off offset:528
	global_load_dwordx4 v[132:135], v[164:165], off offset:512
	v_cndmask_b32_e32 v158, v177, v158, vcc
	v_rsq_f32_e32 v158, v158
	v_pk_fma_f32 v[122:123], v[122:123], v[184:185], v[148:149] op_sel_hi:[1,0,1]
	v_pk_fma_f32 v[126:127], v[126:127], v[184:185], v[152:153] op_sel_hi:[1,0,1]
	v_pk_fma_f32 v[124:125], v[124:125], v[184:185], v[154:155] op_sel_hi:[1,0,1]
	v_mul_f32_e32 v162, 0x45800000, v158
	v_cndmask_b32_e32 v172, v158, v162, vcc
	v_cmp_gt_f32_e32 vcc, s53, v179
	v_mul_f32_e32 v158, 0x4b800000, v179
	v_pk_fma_f32 v[120:121], v[120:121], v[184:185], v[150:151] op_sel_hi:[1,0,1]
	v_cndmask_b32_e32 v158, v179, v158, vcc
	v_rsq_f32_e32 v158, v158
	v_max_f32_e32 v122, 0, v122
	v_max_f32_e32 v124, 0, v124
	v_max_f32_e32 v120, 0, v120
	v_mul_f32_e32 v162, 0x45800000, v158
	v_cndmask_b32_e32 v158, v158, v162, vcc
	v_max_f32_e32 v121, 0, v121
	v_mul_f32_e32 v162, v122, v122
	v_max_f32_e32 v122, 0, v127
	v_mul_f32_e32 v124, v124, v124
	v_mul_f32_e32 v120, v120, v120
	v_max_f32_e32 v125, 0, v125
	v_mul_f32_e32 v121, v121, v121
	v_max_f32_e32 v126, 0, v126
	v_mul_f32_e32 v127, v122, v122
	v_max_f32_e32 v122, 0, v123
	v_mul_f32_e32 v125, v125, v125
	v_mul_f32_e32 v126, v126, v126
	v_mul_f32_e32 v164, v122, v122
	v_cvt_pk_bf16_f32 v122, v124, v125
	v_cvt_pk_bf16_f32 v123, v126, v127
	v_cvt_pk_bf16_f32 v124, v120, v121
	v_lshlrev_b64 v[120:121], 13, v[146:147]
	v_lshl_add_u64 v[120:121], s[8:9], 0, v[120:121]
	v_lshlrev_b64 v[126:127], 1, v[156:157]
	v_pk_fma_f32 v[114:115], v[114:115], v[182:183], v[148:149] op_sel_hi:[1,0,1]
	v_lshl_add_u64 v[120:121], v[120:121], 0, v[126:127]
	v_pk_fma_f32 v[118:119], v[118:119], v[182:183], v[152:153] op_sel_hi:[1,0,1]
	v_pk_fma_f32 v[116:117], v[116:117], v[182:183], v[154:155] op_sel_hi:[1,0,1]
	v_pk_fma_f32 v[112:113], v[112:113], v[182:183], v[150:151] op_sel_hi:[1,0,1]
	v_max_f32_e32 v114, 0, v114
	v_cvt_pk_bf16_f32 v125, v162, v164
	global_store_dwordx4 v[120:121], v[122:125], off
	v_max_f32_e32 v116, 0, v116
	v_max_f32_e32 v112, 0, v112
	v_mul_f32_e32 v122, v114, v114
	v_max_f32_e32 v114, 0, v119
	v_mul_f32_e32 v116, v116, v116
	v_mul_f32_e32 v112, v112, v112
	v_max_f32_e32 v117, 0, v117
	v_max_f32_e32 v113, 0, v113
	v_max_f32_e32 v118, 0, v118
	v_mul_f32_e32 v119, v114, v114
	v_max_f32_e32 v114, 0, v115
	v_mul_f32_e32 v117, v117, v117
	v_mul_f32_e32 v113, v113, v113
	v_mul_f32_e32 v118, v118, v118
	v_mul_f32_e32 v123, v114, v114
	v_cvt_pk_bf16_f32 v114, v116, v117
	v_cvt_pk_bf16_f32 v115, v118, v119
	v_cvt_pk_bf16_f32 v116, v112, v113
	v_or_b32_e32 v112, 16, v146
	v_ashrrev_i32_e32 v113, 31, v112
	v_lshlrev_b64 v[112:113], 13, v[112:113]
	v_lshl_add_u64 v[112:113], s[8:9], 0, v[112:113]
	v_pk_fma_f32 v[106:107], v[106:107], v[180:181], v[148:149] op_sel_hi:[1,0,1]
	v_lshl_add_u64 v[112:113], v[112:113], 0, v[126:127]
	v_pk_fma_f32 v[110:111], v[110:111], v[180:181], v[152:153] op_sel_hi:[1,0,1]
	v_pk_fma_f32 v[108:109], v[108:109], v[180:181], v[154:155] op_sel_hi:[1,0,1]
	v_pk_fma_f32 v[104:105], v[104:105], v[180:181], v[150:151] op_sel_hi:[1,0,1]
	v_max_f32_e32 v106, 0, v106
	v_cvt_pk_bf16_f32 v117, v122, v123
	global_store_dwordx4 v[112:113], v[114:117], off
	v_max_f32_e32 v108, 0, v108
	v_max_f32_e32 v104, 0, v104
	v_mul_f32_e32 v114, v106, v106
	v_max_f32_e32 v106, 0, v111
	v_mul_f32_e32 v108, v108, v108
	v_mul_f32_e32 v104, v104, v104
	v_max_f32_e32 v109, 0, v109
	v_max_f32_e32 v105, 0, v105
	v_max_f32_e32 v110, 0, v110
	v_mul_f32_e32 v111, v106, v106
	v_max_f32_e32 v106, 0, v107
	v_mul_f32_e32 v109, v109, v109
	v_mul_f32_e32 v105, v105, v105
	v_mul_f32_e32 v110, v110, v110
	v_mul_f32_e32 v115, v106, v106
	v_cvt_pk_bf16_f32 v106, v108, v109
	v_cvt_pk_bf16_f32 v107, v110, v111
	v_cvt_pk_bf16_f32 v108, v104, v105
	v_or_b32_e32 v104, 32, v146
	v_ashrrev_i32_e32 v105, 31, v104
	v_lshlrev_b64 v[104:105], 13, v[104:105]
	v_lshl_add_u64 v[104:105], s[8:9], 0, v[104:105]
	v_pk_fma_f32 v[98:99], v[98:99], v[178:179], v[148:149] op_sel_hi:[1,0,1]
	v_lshl_add_u64 v[104:105], v[104:105], 0, v[126:127]
	v_pk_fma_f32 v[102:103], v[102:103], v[178:179], v[152:153] op_sel_hi:[1,0,1]
	v_pk_fma_f32 v[100:101], v[100:101], v[178:179], v[154:155] op_sel_hi:[1,0,1]
	v_pk_fma_f32 v[96:97], v[96:97], v[178:179], v[150:151] op_sel_hi:[1,0,1]
	v_max_f32_e32 v98, 0, v98
	v_cvt_pk_bf16_f32 v109, v114, v115
	global_store_dwordx4 v[104:105], v[106:109], off
	v_max_f32_e32 v100, 0, v100
	v_max_f32_e32 v96, 0, v96
	v_mul_f32_e32 v106, v98, v98
	v_max_f32_e32 v98, 0, v103
	v_mul_f32_e32 v100, v100, v100
	v_mul_f32_e32 v96, v96, v96
	v_max_f32_e32 v101, 0, v101
	v_max_f32_e32 v97, 0, v97
	v_max_f32_e32 v102, 0, v102
	v_mul_f32_e32 v103, v98, v98
	v_max_f32_e32 v98, 0, v99
	v_mul_f32_e32 v101, v101, v101
	v_mul_f32_e32 v97, v97, v97
	v_mul_f32_e32 v102, v102, v102
	v_mul_f32_e32 v107, v98, v98
	v_cvt_pk_bf16_f32 v98, v100, v101
	v_cvt_pk_bf16_f32 v99, v102, v103
	v_cvt_pk_bf16_f32 v100, v96, v97
	v_or_b32_e32 v96, 48, v146
	v_ashrrev_i32_e32 v97, 31, v96
	v_lshlrev_b64 v[96:97], 13, v[96:97]
	v_lshl_add_u64 v[96:97], s[8:9], 0, v[96:97]
	v_pk_fma_f32 v[90:91], v[90:91], v[176:177], v[148:149] op_sel_hi:[1,0,1]
	v_lshl_add_u64 v[96:97], v[96:97], 0, v[126:127]
	v_pk_fma_f32 v[94:95], v[94:95], v[176:177], v[152:153] op_sel_hi:[1,0,1]
	v_max_f32_e32 v90, 0, v90
	v_cvt_pk_bf16_f32 v101, v106, v107
	global_store_dwordx4 v[96:97], v[98:101], off
	v_pk_fma_f32 v[92:93], v[92:93], v[176:177], v[154:155] op_sel_hi:[1,0,1]
	v_max_f32_e32 v94, 0, v94
	v_mul_f32_e32 v98, v90, v90
	v_max_f32_e32 v90, 0, v95
	v_max_f32_e32 v92, 0, v92
	v_max_f32_e32 v93, 0, v93
	v_mul_f32_e32 v94, v94, v94
	v_mul_f32_e32 v95, v90, v90
	v_max_f32_e32 v90, 0, v91
	v_pk_fma_f32 v[88:89], v[88:89], v[176:177], v[150:151] op_sel_hi:[1,0,1]
	v_mul_f32_e32 v92, v92, v92
	v_mul_f32_e32 v93, v93, v93
	v_mul_f32_e32 v99, v90, v90
	v_cvt_pk_bf16_f32 v90, v92, v93
	v_cvt_pk_bf16_f32 v91, v94, v95
	v_add_co_u32_e32 v94, vcc, s1, v120
	v_pk_fma_f32 v[82:83], v[82:83], v[174:175], v[148:149] op_sel_hi:[1,0,1]
	v_max_f32_e32 v88, 0, v88
	v_max_f32_e32 v89, 0, v89
	v_addc_co_u32_e32 v95, vcc, 0, v121, vcc
	v_pk_fma_f32 v[86:87], v[86:87], v[174:175], v[152:153] op_sel_hi:[1,0,1]
	v_max_f32_e32 v82, 0, v82
	v_mul_f32_e32 v88, v88, v88
	v_mul_f32_e32 v89, v89, v89
	v_cvt_pk_bf16_f32 v92, v88, v89
	v_cvt_pk_bf16_f32 v93, v98, v99
	global_store_dwordx4 v[94:95], v[90:93], off
	v_pk_fma_f32 v[84:85], v[84:85], v[174:175], v[154:155] op_sel_hi:[1,0,1]
	v_max_f32_e32 v86, 0, v86
	v_mul_f32_e32 v90, v82, v82
	v_max_f32_e32 v82, 0, v87
	v_max_f32_e32 v84, 0, v84
	v_max_f32_e32 v85, 0, v85
	v_mul_f32_e32 v86, v86, v86
	v_mul_f32_e32 v87, v82, v82
	v_max_f32_e32 v82, 0, v83
	s_mov_b32 s1, 0x120000
	v_pk_fma_f32 v[80:81], v[80:81], v[174:175], v[150:151] op_sel_hi:[1,0,1]
	v_mul_f32_e32 v84, v84, v84
	v_mul_f32_e32 v85, v85, v85
	v_mul_f32_e32 v91, v82, v82
	v_cvt_pk_bf16_f32 v82, v84, v85
	v_cvt_pk_bf16_f32 v83, v86, v87
	v_add_co_u32_e32 v86, vcc, s1, v120
	v_pk_fma_f32 v[74:75], v[74:75], v[172:173], v[148:149] op_sel_hi:[1,0,1]
	v_max_f32_e32 v80, 0, v80
	v_max_f32_e32 v81, 0, v81
	v_addc_co_u32_e32 v87, vcc, 0, v121, vcc
	v_pk_fma_f32 v[78:79], v[78:79], v[172:173], v[152:153] op_sel_hi:[1,0,1]
	v_max_f32_e32 v74, 0, v74
	v_mul_f32_e32 v80, v80, v80
	v_mul_f32_e32 v81, v81, v81
	v_cvt_pk_bf16_f32 v84, v80, v81
	v_cvt_pk_bf16_f32 v85, v90, v91
	global_store_dwordx4 v[86:87], v[82:85], off
	v_pk_fma_f32 v[76:77], v[76:77], v[172:173], v[154:155] op_sel_hi:[1,0,1]
	v_max_f32_e32 v78, 0, v78
	v_mul_f32_e32 v82, v74, v74
	v_max_f32_e32 v74, 0, v79
	v_max_f32_e32 v76, 0, v76
	v_max_f32_e32 v77, 0, v77
	v_mul_f32_e32 v78, v78, v78
	v_mul_f32_e32 v79, v74, v74
	v_max_f32_e32 v74, 0, v75
	s_mov_b32 s1, 0x140000
	v_pk_fma_f32 v[72:73], v[72:73], v[172:173], v[150:151] op_sel_hi:[1,0,1]
	v_mul_f32_e32 v76, v76, v76
	v_mul_f32_e32 v77, v77, v77
	v_mul_f32_e32 v83, v74, v74
	v_cvt_pk_bf16_f32 v74, v76, v77
	v_cvt_pk_bf16_f32 v75, v78, v79
	v_add_co_u32_e32 v78, vcc, s1, v120
	v_pk_fma_f32 v[58:59], v[58:59], v[158:159], v[148:149] op_sel_hi:[1,0,1]
	v_max_f32_e32 v72, 0, v72
	v_max_f32_e32 v73, 0, v73
	v_addc_co_u32_e32 v79, vcc, 0, v121, vcc
	v_pk_fma_f32 v[62:63], v[62:63], v[158:159], v[152:153] op_sel_hi:[1,0,1]
	v_max_f32_e32 v58, 0, v58
	v_mul_f32_e32 v72, v72, v72
	v_mul_f32_e32 v73, v73, v73
	v_cvt_pk_bf16_f32 v76, v72, v73
	v_cvt_pk_bf16_f32 v77, v82, v83
	global_store_dwordx4 v[78:79], v[74:77], off
	v_pk_fma_f32 v[60:61], v[60:61], v[158:159], v[154:155] op_sel_hi:[1,0,1]
	v_max_f32_e32 v62, 0, v62
	v_mul_f32_e32 v74, v58, v58
	v_max_f32_e32 v58, 0, v63
	v_max_f32_e32 v60, 0, v60
	v_max_f32_e32 v61, 0, v61
	v_mul_f32_e32 v62, v62, v62
	v_mul_f32_e32 v63, v58, v58
	v_max_f32_e32 v58, 0, v59
	s_mov_b32 s1, 0x160000
	v_pk_fma_f32 v[56:57], v[56:57], v[158:159], v[150:151] op_sel_hi:[1,0,1]
	v_mul_f32_e32 v60, v60, v60
	v_mul_f32_e32 v61, v61, v61
	v_mul_f32_e32 v75, v58, v58
	v_cvt_pk_bf16_f32 v58, v60, v61
	v_cvt_pk_bf16_f32 v59, v62, v63
	v_add_co_u32_e32 v62, vcc, s1, v120
	s_waitcnt vmcnt(7)
	v_pk_add_f32 v[134:135], v[134:135], 0 op_sel_hi:[1,0]
	v_max_f32_e32 v56, 0, v56
	v_max_f32_e32 v57, 0, v57
	v_addc_co_u32_e32 v63, vcc, 0, v121, vcc
	v_pk_add_f32 v[130:131], v[130:131], 0 op_sel_hi:[1,0]
	v_mul_f32_e32 v56, v56, v56
	v_mul_f32_e32 v57, v57, v57
	v_cvt_pk_bf16_f32 v60, v56, v57
	v_cvt_pk_bf16_f32 v61, v74, v75
	global_store_dwordx4 v[62:63], v[58:61], off
	v_pk_fma_f32 v[62:63], v[66:67], v[184:185], v[130:131] op_sel_hi:[1,0,1]
	v_pk_add_f32 v[132:133], v[132:133], 0 op_sel_hi:[1,0]
	v_pk_fma_f32 v[58:59], v[70:71], v[184:185], v[134:135] op_sel_hi:[1,0,1]
	v_pk_add_f32 v[128:129], v[128:129], 0 op_sel_hi:[1,0]
	v_max_f32_e32 v58, 0, v58
	v_mul_f32_e32 v66, v58, v58
	v_max_f32_e32 v58, 0, v62
	v_pk_fma_f32 v[60:61], v[68:69], v[184:185], v[132:133] op_sel_hi:[1,0,1]
	v_mul_f32_e32 v62, v58, v58
	v_max_f32_e32 v58, 0, v59
	v_pk_fma_f32 v[64:65], v[64:65], v[184:185], v[128:129] op_sel_hi:[1,0,1]
	v_max_f32_e32 v60, 0, v60
	v_max_f32_e32 v61, 0, v61
	v_mul_f32_e32 v59, v58, v58
	v_max_f32_e32 v58, 0, v63
	v_pk_fma_f32 v[48:49], v[48:49], v[182:183], v[128:129] op_sel_hi:[1,0,1]
	v_mul_f32_e32 v60, v60, v60
	v_max_f32_e32 v64, 0, v64
	v_mul_f32_e32 v61, v61, v61
	v_max_f32_e32 v65, 0, v65
	v_mul_f32_e32 v63, v58, v58
	v_cvt_pk_bf16_f32 v58, v60, v61
	v_pk_fma_f32 v[52:53], v[52:53], v[182:183], v[132:133] op_sel_hi:[1,0,1]
	v_pk_fma_f32 v[50:51], v[50:51], v[182:183], v[130:131] op_sel_hi:[1,0,1]
	v_max_f32_e32 v48, 0, v48
	v_mul_f32_e32 v64, v64, v64
	v_mul_f32_e32 v65, v65, v65
	v_cvt_pk_bf16_f32 v59, v66, v59
	v_cvt_pk_bf16_f32 v60, v64, v65
	v_cvt_pk_bf16_f32 v61, v62, v63
	global_store_dwordx4 v[120:121], v[58:61], off offset:256
	v_pk_fma_f32 v[54:55], v[54:55], v[182:183], v[134:135] op_sel_hi:[1,0,1]
	v_max_f32_e32 v49, 0, v49
	v_mul_f32_e32 v58, v48, v48
	v_max_f32_e32 v48, 0, v53
	v_max_f32_e32 v50, 0, v50
	v_max_f32_e32 v52, 0, v52
	v_mul_f32_e32 v48, v48, v48
	v_mul_f32_e32 v53, v49, v49
	v_max_f32_e32 v49, 0, v54
	v_mul_f32_e32 v54, v50, v50
	v_max_f32_e32 v50, 0, v55
	v_max_f32_e32 v51, 0, v51
	v_pk_fma_f32 v[40:41], v[40:41], v[180:181], v[128:129] op_sel_hi:[1,0,1]
	v_mul_f32_e32 v52, v52, v52
	v_mul_f32_e32 v49, v49, v49
	v_mul_f32_e32 v50, v50, v50
	v_mul_f32_e32 v51, v51, v51
	v_cvt_pk_bf16_f32 v48, v52, v48
	v_pk_fma_f32 v[44:45], v[44:45], v[180:181], v[132:133] op_sel_hi:[1,0,1]
	v_pk_fma_f32 v[42:43], v[42:43], v[180:181], v[130:131] op_sel_hi:[1,0,1]
	v_max_f32_e32 v40, 0, v40
	v_cvt_pk_bf16_f32 v49, v49, v50
	v_cvt_pk_bf16_f32 v50, v58, v53
	v_cvt_pk_bf16_f32 v51, v54, v51
	global_store_dwordx4 v[112:113], v[48:51], off offset:256
	v_pk_fma_f32 v[46:47], v[46:47], v[180:181], v[134:135] op_sel_hi:[1,0,1]
	v_max_f32_e32 v41, 0, v41
	v_mul_f32_e32 v48, v40, v40
	v_max_f32_e32 v40, 0, v45
	v_max_f32_e32 v42, 0, v42
	v_max_f32_e32 v44, 0, v44
	v_mul_f32_e32 v40, v40, v40
	v_mul_f32_e32 v45, v41, v41
	v_max_f32_e32 v41, 0, v46
	v_mul_f32_e32 v46, v42, v42
	v_max_f32_e32 v42, 0, v47
	v_max_f32_e32 v43, 0, v43
	v_pk_fma_f32 v[32:33], v[32:33], v[178:179], v[128:129] op_sel_hi:[1,0,1]
	v_mul_f32_e32 v44, v44, v44
	v_mul_f32_e32 v41, v41, v41
	v_mul_f32_e32 v42, v42, v42
	v_mul_f32_e32 v43, v43, v43
	v_cvt_pk_bf16_f32 v40, v44, v40
	v_pk_fma_f32 v[36:37], v[36:37], v[178:179], v[132:133] op_sel_hi:[1,0,1]
	v_pk_fma_f32 v[34:35], v[34:35], v[178:179], v[130:131] op_sel_hi:[1,0,1]
	v_max_f32_e32 v32, 0, v32
	v_cvt_pk_bf16_f32 v41, v41, v42
	v_cvt_pk_bf16_f32 v42, v48, v45
	v_cvt_pk_bf16_f32 v43, v46, v43
	global_store_dwordx4 v[104:105], v[40:43], off offset:256
	v_pk_fma_f32 v[38:39], v[38:39], v[178:179], v[134:135] op_sel_hi:[1,0,1]
	v_max_f32_e32 v33, 0, v33
	v_mul_f32_e32 v40, v32, v32
	v_max_f32_e32 v32, 0, v37
	v_max_f32_e32 v34, 0, v34
	v_max_f32_e32 v36, 0, v36
	v_mul_f32_e32 v32, v32, v32
	v_mul_f32_e32 v37, v33, v33
	v_max_f32_e32 v33, 0, v38
	v_mul_f32_e32 v38, v34, v34
	v_max_f32_e32 v34, 0, v39
	v_max_f32_e32 v35, 0, v35
	v_pk_fma_f32 v[24:25], v[24:25], v[176:177], v[128:129] op_sel_hi:[1,0,1]
	v_mul_f32_e32 v36, v36, v36
	v_mul_f32_e32 v33, v33, v33
	v_mul_f32_e32 v34, v34, v34
	v_mul_f32_e32 v35, v35, v35
	v_cvt_pk_bf16_f32 v32, v36, v32
	v_pk_fma_f32 v[28:29], v[28:29], v[176:177], v[132:133] op_sel_hi:[1,0,1]
	v_pk_fma_f32 v[26:27], v[26:27], v[176:177], v[130:131] op_sel_hi:[1,0,1]
	v_max_f32_e32 v24, 0, v24
	v_cvt_pk_bf16_f32 v33, v33, v34
	v_cvt_pk_bf16_f32 v34, v40, v37
	v_cvt_pk_bf16_f32 v35, v38, v35
	global_store_dwordx4 v[96:97], v[32:35], off offset:256
	v_pk_fma_f32 v[30:31], v[30:31], v[176:177], v[134:135] op_sel_hi:[1,0,1]
	v_max_f32_e32 v25, 0, v25
	v_mul_f32_e32 v32, v24, v24
	v_max_f32_e32 v24, 0, v29
	v_max_f32_e32 v26, 0, v26
	s_mov_b64 s[8:9], 0x100000
	v_max_f32_e32 v28, 0, v28
	v_mul_f32_e32 v24, v24, v24
	v_mul_f32_e32 v29, v25, v25
	v_max_f32_e32 v25, 0, v30
	v_mul_f32_e32 v30, v26, v26
	v_max_f32_e32 v26, 0, v31
	v_max_f32_e32 v27, 0, v27
	v_pk_fma_f32 v[16:17], v[16:17], v[174:175], v[128:129] op_sel_hi:[1,0,1]
	v_lshl_add_u64 v[88:89], v[120:121], 0, s[8:9]
	v_mul_f32_e32 v28, v28, v28
	v_mul_f32_e32 v25, v25, v25
	v_mul_f32_e32 v26, v26, v26
	v_mul_f32_e32 v27, v27, v27
	v_cvt_pk_bf16_f32 v24, v28, v24
	v_pk_fma_f32 v[20:21], v[20:21], v[174:175], v[132:133] op_sel_hi:[1,0,1]
	v_pk_fma_f32 v[18:19], v[18:19], v[174:175], v[130:131] op_sel_hi:[1,0,1]
	v_max_f32_e32 v16, 0, v16
	v_cvt_pk_bf16_f32 v25, v25, v26
	v_cvt_pk_bf16_f32 v26, v32, v29
	v_cvt_pk_bf16_f32 v27, v30, v27
	global_store_dwordx4 v[88:89], v[24:27], off offset:256
	v_pk_fma_f32 v[22:23], v[22:23], v[174:175], v[134:135] op_sel_hi:[1,0,1]
	v_max_f32_e32 v17, 0, v17
	v_mul_f32_e32 v24, v16, v16
	v_max_f32_e32 v16, 0, v21
	v_max_f32_e32 v18, 0, v18
	s_mov_b64 s[8:9], 0x120000
	v_max_f32_e32 v20, 0, v20
	v_mul_f32_e32 v16, v16, v16
	v_mul_f32_e32 v21, v17, v17
	v_max_f32_e32 v17, 0, v22
	v_mul_f32_e32 v22, v18, v18
	v_max_f32_e32 v18, 0, v23
	v_max_f32_e32 v19, 0, v19
	v_pk_fma_f32 v[8:9], v[8:9], v[172:173], v[128:129] op_sel_hi:[1,0,1]
	v_lshl_add_u64 v[80:81], v[120:121], 0, s[8:9]
	v_mul_f32_e32 v20, v20, v20
	v_mul_f32_e32 v17, v17, v17
	v_mul_f32_e32 v18, v18, v18
	v_mul_f32_e32 v19, v19, v19
	v_cvt_pk_bf16_f32 v16, v20, v16
	v_pk_fma_f32 v[12:13], v[12:13], v[172:173], v[132:133] op_sel_hi:[1,0,1]
	v_pk_fma_f32 v[10:11], v[10:11], v[172:173], v[130:131] op_sel_hi:[1,0,1]
	v_max_f32_e32 v8, 0, v8
	v_cvt_pk_bf16_f32 v17, v17, v18
	v_cvt_pk_bf16_f32 v18, v24, v21
	v_cvt_pk_bf16_f32 v19, v22, v19
	global_store_dwordx4 v[80:81], v[16:19], off offset:256
	v_pk_fma_f32 v[14:15], v[14:15], v[172:173], v[134:135] op_sel_hi:[1,0,1]
	v_max_f32_e32 v9, 0, v9
	v_mul_f32_e32 v16, v8, v8
	v_max_f32_e32 v8, 0, v13
	v_max_f32_e32 v10, 0, v10
	s_mov_b64 s[8:9], 0x140000
	v_max_f32_e32 v12, 0, v12
	v_mul_f32_e32 v8, v8, v8
	v_mul_f32_e32 v13, v9, v9
	v_max_f32_e32 v9, 0, v14
	v_mul_f32_e32 v14, v10, v10
	v_max_f32_e32 v10, 0, v15
	v_max_f32_e32 v11, 0, v11
	v_pk_fma_f32 v[2:3], v[2:3], v[158:159], v[130:131] op_sel_hi:[1,0,1]
	v_pk_fma_f32 v[0:1], v[0:1], v[158:159], v[128:129] op_sel_hi:[1,0,1]
	v_lshl_add_u64 v[72:73], v[120:121], 0, s[8:9]
	v_mul_f32_e32 v12, v12, v12
	v_mul_f32_e32 v9, v9, v9
	v_mul_f32_e32 v10, v10, v10
	v_mul_f32_e32 v11, v11, v11
	v_cvt_pk_bf16_f32 v8, v12, v8
	v_pk_fma_f32 v[6:7], v[6:7], v[158:159], v[134:135] op_sel_hi:[1,0,1]
	v_pk_fma_f32 v[4:5], v[4:5], v[158:159], v[132:133] op_sel_hi:[1,0,1]
	v_max_f32_e32 v0, 0, v0
	v_max_f32_e32 v1, 0, v1
	v_max_f32_e32 v2, 0, v2
	s_mov_b64 s[8:9], 0x160000
	v_cvt_pk_bf16_f32 v9, v9, v10
	v_cvt_pk_bf16_f32 v10, v16, v13
	v_cvt_pk_bf16_f32 v11, v14, v11
	global_store_dwordx4 v[72:73], v[8:11], off offset:256
	v_max_f32_e32 v3, 0, v3
	v_lshl_add_u64 v[56:57], v[120:121], 0, s[8:9]
	v_mul_f32_e32 v8, v0, v0
	v_max_f32_e32 v0, 0, v5
	v_mul_f32_e32 v5, v1, v1
	v_max_f32_e32 v1, 0, v6
	v_mul_f32_e32 v6, v2, v2
	v_max_f32_e32 v2, 0, v7
	v_max_f32_e32 v4, 0, v4
	v_mul_f32_e32 v0, v0, v0
	v_mul_f32_e32 v1, v1, v1
	v_mul_f32_e32 v2, v2, v2
	v_mul_f32_e32 v3, v3, v3
	s_and_b64 vcc, exec, s[2:3]
	s_mov_b64 s[8:9], s[58:59]
	v_mul_f32_e32 v4, v4, v4
	v_cvt_pk_bf16_f32 v0, v4, v0
	v_cvt_pk_bf16_f32 v1, v1, v2
	v_cvt_pk_bf16_f32 v2, v8, v5
	v_cvt_pk_bf16_f32 v3, v6, v3
	global_store_dwordx4 v[56:57], v[0:3], off offset:256
	s_cbranch_vccz .LBB0_123
	s_waitcnt vmcnt(0)
	s_mov_b32 s90, s62
	s_cmpk_gt_u32 s36, 0xff
	s_cbranch_scc1 .LBB0_134
	s_barrier

.LBB0_350:
	s_add_u32 s8, s60, 0xfffc0080
	s_addc_u32 s9, s61, -1
	s_add_i32 s16, 0, 0x10000
	v_add_u32_e32 v150, s16, v168
	ds_read_b128 v[128:131], v150
	ds_read_b128 v[132:135], v150 offset:1024
	ds_read_b128 v[146:149], v150 offset:2048
	ds_read_b128 v[150:153], v150 offset:3072
	s_cmp_eq_u32 s15, 12
	s_cselect_b32 s9, s5, s9
	s_cselect_b32 s8, s10, s8
	s_cselect_b32 s63, s1, s14
	s_cselect_b32 s62, s12, s13
	s_cbranch_scc0 .Lpf350_skip
	v_readlane_b32 s22, v249, 24
	v_readlane_b32 s23, v249, 25
	v_readlane_b32 s24, v249, 26
	v_readlane_b32 s25, v249, 27
	v_lshl_add_u32 v246, s65, 8, v159
	v_lshl_or_b32 v247, s66, 8, v169
	s_ashr_i32 s26, s65, 5
	s_lshl_b32 s26, s26, 14
	v_lshlrev_b32_e32 v246, 3, v246
	v_lshlrev_b32_e32 v247, 2, v247
	s_add_u32 s24, s24, s26
	s_addc_u32 s25, s25, 0
	global_load_dwordx2 v[242:243], v246, s[22:23]
	global_load_dwordx2 v[244:245], v246, s[22:23] offset:128
	global_load_dwordx2 v[164:165], v246, s[22:23] offset:256
	global_load_dwordx2 v[166:167], v246, s[22:23] offset:384
	global_load_dwordx2 v[224:225], v246, s[22:23] offset:1024
	global_load_dwordx2 v[226:227], v246, s[22:23] offset:1152
	global_load_dwordx2 v[228:229], v246, s[22:23] offset:1280
	global_load_dwordx2 v[230:231], v246, s[22:23] offset:1408
	global_load_dwordx4 v[232:235], v247, s[24:25] offset:16
	global_load_dwordx4 v[236:239], v247, s[24:25]
.Lpf350_skip:
	v_lshl_add_u64 v[200:201], s[60:61], 0, v[142:143]
	s_add_i32 m0, s38, 0xc000
	ds_read_b128 v[154:157], v170
	ds_read_b128 v[172:175], v170 offset:1024
	ds_read_b128 v[176:179], v170 offset:2048
	ds_read_b128 v[180:183], v170 offset:3072
	ds_read_b128 v[184:187], v170 offset:4096
	ds_read_b128 v[188:191], v170 offset:5120
	ds_read_b128 v[192:195], v170 offset:6144
	ds_read_b128 v[196:199], v170 offset:7168
	global_load_lds_dwordx4 v[200:201], off
	v_lshl_add_u64 v[200:201], s[60:61], 0, v[144:145]
	s_add_i32 m0, s38, 0xe000
	s_nop 0
	global_load_lds_dwordx4 v[200:201], off
	s_waitcnt lgkmcnt(8)
	s_barrier
	s_waitcnt lgkmcnt(0)
	s_setprio 1
	s_waitcnt lgkmcnt(0)
	v_mfma_f32_16x16x32_bf16 v[124:127], v[128:131], v[154:157], v[124:127]
	v_mfma_f32_16x16x32_bf16 v[120:123], v[146:149], v[154:157], v[120:123]
	v_mfma_f32_16x16x32_bf16 v[116:119], v[128:131], v[176:179], v[116:119]
	v_mfma_f32_16x16x32_bf16 v[112:115], v[146:149], v[176:179], v[112:115]
	v_mfma_f32_16x16x32_bf16 v[108:111], v[128:131], v[184:187], v[108:111]
	v_mfma_f32_16x16x32_bf16 v[104:107], v[146:149], v[184:187], v[104:107]
	v_mfma_f32_16x16x32_bf16 v[100:103], v[128:131], v[192:195], v[100:103]
	v_mfma_f32_16x16x32_bf16 v[96:99], v[146:149], v[192:195], v[96:99]
	v_mfma_f32_16x16x32_bf16 v[124:127], v[132:135], v[172:175], v[124:127]
	v_mfma_f32_16x16x32_bf16 v[120:123], v[150:153], v[172:175], v[120:123]
	v_mfma_f32_16x16x32_bf16 v[116:119], v[132:135], v[180:183], v[116:119]
	v_mfma_f32_16x16x32_bf16 v[112:115], v[150:153], v[180:183], v[112:115]
	v_mfma_f32_16x16x32_bf16 v[108:111], v[132:135], v[188:191], v[108:111]
	v_mfma_f32_16x16x32_bf16 v[104:107], v[150:153], v[188:191], v[104:107]
	v_mfma_f32_16x16x32_bf16 v[100:103], v[132:135], v[196:199], v[100:103]
	v_mfma_f32_16x16x32_bf16 v[96:99], v[150:153], v[196:199], v[96:99]
	s_setprio 0
	s_barrier
	s_add_i32 s18, 0, 0x14000
	s_add_i32 s16, s16, s37
	v_add_u32_e32 v158, s18, v168
	v_lshl_add_u64 v[216:217], s[62:63], 0, v[160:161]
	s_mov_b32 m0, s16
	ds_read_b128 v[200:203], v158
	ds_read_b128 v[204:207], v158 offset:1024
	ds_read_b128 v[208:211], v158 offset:2048
	ds_read_b128 v[212:215], v158 offset:3072
	global_load_lds_dwordx4 v[216:217], off
	v_lshl_add_u64 v[218:219], s[62:63], 0, v[136:137]
	s_add_i32 m0, s16, 0x2000
	s_nop 0
	global_load_lds_dwordx4 v[218:219], off
	s_barrier
	s_waitcnt lgkmcnt(0)
	s_setprio 1
	s_waitcnt lgkmcnt(0)
	v_mfma_f32_16x16x32_bf16 v[68:71], v[200:203], v[154:157], v[68:71]
	v_mfma_f32_16x16x32_bf16 v[64:67], v[208:211], v[154:157], v[64:67]
	v_mfma_f32_16x16x32_bf16 v[52:55], v[200:203], v[176:179], v[52:55]
	v_mfma_f32_16x16x32_bf16 v[48:51], v[208:211], v[176:179], v[48:51]
	v_mfma_f32_16x16x32_bf16 v[44:47], v[200:203], v[184:187], v[44:47]
	v_mfma_f32_16x16x32_bf16 v[40:43], v[208:211], v[184:187], v[40:43]
	v_mfma_f32_16x16x32_bf16 v[36:39], v[200:203], v[192:195], v[36:39]
	v_mfma_f32_16x16x32_bf16 v[32:35], v[208:211], v[192:195], v[32:35]
	v_mfma_f32_16x16x32_bf16 v[68:71], v[204:207], v[172:175], v[68:71]
	v_mfma_f32_16x16x32_bf16 v[64:67], v[212:215], v[172:175], v[64:67]
	v_mfma_f32_16x16x32_bf16 v[52:55], v[204:207], v[180:183], v[52:55]
	v_mfma_f32_16x16x32_bf16 v[48:51], v[212:215], v[180:183], v[48:51]
	v_mfma_f32_16x16x32_bf16 v[44:47], v[204:207], v[188:191], v[44:47]
	v_mfma_f32_16x16x32_bf16 v[40:43], v[212:215], v[188:191], v[40:43]
	v_mfma_f32_16x16x32_bf16 v[36:39], v[204:207], v[196:199], v[36:39]
	v_mfma_f32_16x16x32_bf16 v[32:35], v[212:215], v[196:199], v[32:35]
	s_setprio 0
	s_mov_b32 m0, s38
	v_lshl_add_u64 v[220:221], s[8:9], 0, v[140:141]
	s_barrier
	ds_read_b128 v[154:157], v170 offset:16384
	ds_read_b128 v[172:175], v170 offset:17408
	ds_read_b128 v[176:179], v170 offset:18432
	ds_read_b128 v[180:183], v170 offset:19456
	ds_read_b128 v[184:187], v170 offset:20480
	ds_read_b128 v[188:191], v170 offset:21504
	ds_read_b128 v[192:195], v170 offset:22528
	ds_read_b128 v[196:199], v170 offset:23552
	global_load_lds_dwordx4 v[220:221], off
	v_lshl_add_u64 v[222:223], s[8:9], 0, v[138:139]
	s_mov_b32 m0, s39
	s_nop 0
	global_load_lds_dwordx4 v[222:223], off
	s_barrier
	s_waitcnt lgkmcnt(0)
	s_setprio 1
	s_waitcnt lgkmcnt(0)
	v_mfma_f32_16x16x32_bf16 v[92:95], v[128:131], v[154:157], v[92:95]
	v_mfma_f32_16x16x32_bf16 v[88:91], v[146:149], v[154:157], v[88:91]
	v_mfma_f32_16x16x32_bf16 v[84:87], v[128:131], v[176:179], v[84:87]
	v_mfma_f32_16x16x32_bf16 v[80:83], v[146:149], v[176:179], v[80:83]
	v_mfma_f32_16x16x32_bf16 v[76:79], v[128:131], v[184:187], v[76:79]
	v_mfma_f32_16x16x32_bf16 v[72:75], v[146:149], v[184:187], v[72:75]
	v_mfma_f32_16x16x32_bf16 v[60:63], v[128:131], v[192:195], v[60:63]
	v_mfma_f32_16x16x32_bf16 v[56:59], v[146:149], v[192:195], v[56:59]
	v_mfma_f32_16x16x32_bf16 v[92:95], v[132:135], v[172:175], v[92:95]
	v_mfma_f32_16x16x32_bf16 v[88:91], v[150:153], v[172:175], v[88:91]
	v_mfma_f32_16x16x32_bf16 v[84:87], v[132:135], v[180:183], v[84:87]
	v_mfma_f32_16x16x32_bf16 v[80:83], v[150:153], v[180:183], v[80:83]
	v_mfma_f32_16x16x32_bf16 v[76:79], v[132:135], v[188:191], v[76:79]
	v_mfma_f32_16x16x32_bf16 v[72:75], v[150:153], v[188:191], v[72:75]
	v_mfma_f32_16x16x32_bf16 v[60:63], v[132:135], v[196:199], v[60:63]
	v_mfma_f32_16x16x32_bf16 v[56:59], v[150:153], v[196:199], v[56:59]
	s_setprio 0
	s_barrier
	s_add_u32 s16, s62, 0x40000
	s_addc_u32 s17, s63, 0
	s_add_i32 s18, s18, s37
	v_lshl_add_u64 v[128:129], s[16:17], 0, v[160:161]
	s_mov_b32 m0, s18
	s_nop 0
	global_load_lds_dwordx4 v[128:129], off
	v_lshl_add_u64 v[128:129], s[16:17], 0, v[136:137]
	s_add_i32 m0, s18, 0x2000
	s_nop 0
	global_load_lds_dwordx4 v[128:129], off
	s_waitcnt vmcnt(6)
	s_barrier
	s_setprio 1
	v_mfma_f32_16x16x32_bf16 v[28:31], v[200:203], v[154:157], v[28:31]
	v_mfma_f32_16x16x32_bf16 v[24:27], v[208:211], v[154:157], v[24:27]
	v_mfma_f32_16x16x32_bf16 v[20:23], v[200:203], v[176:179], v[20:23]
	v_mfma_f32_16x16x32_bf16 v[16:19], v[208:211], v[176:179], v[16:19]
	v_mfma_f32_16x16x32_bf16 v[12:15], v[200:203], v[184:187], v[12:15]
	v_mfma_f32_16x16x32_bf16 v[8:11], v[208:211], v[184:187], v[8:11]
	v_mfma_f32_16x16x32_bf16 v[4:7], v[200:203], v[192:195], v[4:7]
	v_mfma_f32_16x16x32_bf16 v[0:3], v[208:211], v[192:195], v[0:3]
	v_mfma_f32_16x16x32_bf16 v[28:31], v[204:207], v[172:175], v[28:31]
	v_mfma_f32_16x16x32_bf16 v[24:27], v[212:215], v[172:175], v[24:27]
	v_mfma_f32_16x16x32_bf16 v[20:23], v[204:207], v[180:183], v[20:23]
	v_mfma_f32_16x16x32_bf16 v[16:19], v[212:215], v[180:183], v[16:19]
	v_mfma_f32_16x16x32_bf16 v[12:15], v[204:207], v[188:191], v[12:15]
	v_mfma_f32_16x16x32_bf16 v[8:11], v[212:215], v[188:191], v[8:11]
	v_mfma_f32_16x16x32_bf16 v[4:7], v[204:207], v[196:199], v[4:7]
	v_mfma_f32_16x16x32_bf16 v[0:3], v[212:215], v[196:199], v[0:3]
	s_setprio 0
	s_add_i32 s16, 0, 0x18000
	v_add_u32_e32 v150, s16, v168
	s_barrier
	ds_read_b128 v[128:131], v150
	ds_read_b128 v[132:135], v150 offset:1024
	ds_read_b128 v[146:149], v150 offset:2048
	ds_read_b128 v[150:153], v150 offset:3072
	s_add_u32 s8, s8, 0x40000
	s_addc_u32 s9, s9, 0
	s_mov_b32 m0, s40
	v_lshl_add_u64 v[200:201], s[8:9], 0, v[140:141]
	ds_read_b128 v[154:157], v170 offset:32768
	ds_read_b128 v[172:175], v170 offset:33792
	ds_read_b128 v[176:179], v170 offset:34816
	ds_read_b128 v[180:183], v170 offset:35840
	ds_read_b128 v[184:187], v170 offset:36864
	ds_read_b128 v[188:191], v170 offset:37888
	ds_read_b128 v[192:195], v170 offset:38912
	ds_read_b128 v[196:199], v170 offset:39936
	global_load_lds_dwordx4 v[200:201], off
	v_lshl_add_u64 v[200:201], s[8:9], 0, v[138:139]
	s_mov_b32 m0, s41
	s_nop 0
	global_load_lds_dwordx4 v[200:201], off
	s_waitcnt lgkmcnt(8)
	s_barrier
	s_waitcnt lgkmcnt(0)
	s_setprio 1
	s_waitcnt lgkmcnt(0)
	v_mfma_f32_16x16x32_bf16 v[124:127], v[128:131], v[154:157], v[124:127]
	v_mfma_f32_16x16x32_bf16 v[120:123], v[146:149], v[154:157], v[120:123]
	v_mfma_f32_16x16x32_bf16 v[116:119], v[128:131], v[176:179], v[116:119]
	v_mfma_f32_16x16x32_bf16 v[112:115], v[146:149], v[176:179], v[112:115]
	v_mfma_f32_16x16x32_bf16 v[108:111], v[128:131], v[184:187], v[108:111]
	v_mfma_f32_16x16x32_bf16 v[104:107], v[146:149], v[184:187], v[104:107]
	v_mfma_f32_16x16x32_bf16 v[100:103], v[128:131], v[192:195], v[100:103]
	v_mfma_f32_16x16x32_bf16 v[96:99], v[146:149], v[192:195], v[96:99]
	v_mfma_f32_16x16x32_bf16 v[124:127], v[132:135], v[172:175], v[124:127]
	v_mfma_f32_16x16x32_bf16 v[120:123], v[150:153], v[172:175], v[120:123]
	v_mfma_f32_16x16x32_bf16 v[116:119], v[132:135], v[180:183], v[116:119]
	v_mfma_f32_16x16x32_bf16 v[112:115], v[150:153], v[180:183], v[112:115]
	v_mfma_f32_16x16x32_bf16 v[108:111], v[132:135], v[188:191], v[108:111]
	v_mfma_f32_16x16x32_bf16 v[104:107], v[150:153], v[188:191], v[104:107]
	v_mfma_f32_16x16x32_bf16 v[100:103], v[132:135], v[196:199], v[100:103]
	v_mfma_f32_16x16x32_bf16 v[96:99], v[150:153], v[196:199], v[96:99]
	s_setprio 0
	s_barrier
	s_add_i32 s17, 0, 0x1c000
	s_add_i32 s8, s16, s37
	v_add_u32_e32 v158, s17, v168
	v_lshl_add_u64 v[216:217], v[216:217], 0, s[74:75]
	s_mov_b32 m0, s8
	ds_read_b128 v[200:203], v158
	ds_read_b128 v[204:207], v158 offset:1024
	ds_read_b128 v[208:211], v158 offset:2048
	ds_read_b128 v[212:215], v158 offset:3072
	global_load_lds_dwordx4 v[216:217], off
	v_lshl_add_u64 v[216:217], v[218:219], 0, s[74:75]
	s_add_i32 m0, s8, 0x2000
	s_nop 0
	global_load_lds_dwordx4 v[216:217], off
	s_barrier
	s_waitcnt lgkmcnt(0)
	s_setprio 1
	s_waitcnt lgkmcnt(0)
	v_mfma_f32_16x16x32_bf16 v[68:71], v[200:203], v[154:157], v[68:71]
	v_mfma_f32_16x16x32_bf16 v[64:67], v[208:211], v[154:157], v[64:67]
	v_mfma_f32_16x16x32_bf16 v[52:55], v[200:203], v[176:179], v[52:55]
	v_mfma_f32_16x16x32_bf16 v[48:51], v[208:211], v[176:179], v[48:51]
	v_mfma_f32_16x16x32_bf16 v[44:47], v[200:203], v[184:187], v[44:47]
	v_mfma_f32_16x16x32_bf16 v[40:43], v[208:211], v[184:187], v[40:43]
	v_mfma_f32_16x16x32_bf16 v[36:39], v[200:203], v[192:195], v[36:39]
	v_mfma_f32_16x16x32_bf16 v[32:35], v[208:211], v[192:195], v[32:35]
	v_mfma_f32_16x16x32_bf16 v[68:71], v[204:207], v[172:175], v[68:71]
	v_mfma_f32_16x16x32_bf16 v[64:67], v[212:215], v[172:175], v[64:67]
	v_mfma_f32_16x16x32_bf16 v[52:55], v[204:207], v[180:183], v[52:55]
	v_mfma_f32_16x16x32_bf16 v[48:51], v[212:215], v[180:183], v[48:51]
	v_mfma_f32_16x16x32_bf16 v[44:47], v[204:207], v[188:191], v[44:47]
	v_mfma_f32_16x16x32_bf16 v[40:43], v[212:215], v[188:191], v[40:43]
	v_mfma_f32_16x16x32_bf16 v[36:39], v[204:207], v[196:199], v[36:39]
	v_mfma_f32_16x16x32_bf16 v[32:35], v[212:215], v[196:199], v[32:35]
	s_setprio 0
	s_mov_b32 m0, s42
	v_lshl_add_u64 v[216:217], v[220:221], 0, s[74:75]
	s_barrier
	ds_read_b128 v[154:157], v170 offset:49152
	ds_read_b128 v[172:175], v170 offset:50176
	ds_read_b128 v[176:179], v170 offset:51200
	ds_read_b128 v[180:183], v170 offset:52224
	ds_read_b128 v[184:187], v170 offset:53248
	ds_read_b128 v[188:191], v170 offset:54272
	ds_read_b128 v[192:195], v170 offset:55296
	ds_read_b128 v[196:199], v170 offset:56320
	global_load_lds_dwordx4 v[216:217], off
	v_lshl_add_u64 v[216:217], v[222:223], 0, s[74:75]
	s_mov_b32 m0, s43
	s_nop 0
	global_load_lds_dwordx4 v[216:217], off
	s_barrier
	s_waitcnt lgkmcnt(0)
	s_setprio 1
	s_waitcnt lgkmcnt(0)
	v_mfma_f32_16x16x32_bf16 v[92:95], v[128:131], v[154:157], v[92:95]
	v_mfma_f32_16x16x32_bf16 v[88:91], v[146:149], v[154:157], v[88:91]
	v_mfma_f32_16x16x32_bf16 v[84:87], v[128:131], v[176:179], v[84:87]
	v_mfma_f32_16x16x32_bf16 v[80:83], v[146:149], v[176:179], v[80:83]
	v_mfma_f32_16x16x32_bf16 v[76:79], v[128:131], v[184:187], v[76:79]
	v_mfma_f32_16x16x32_bf16 v[72:75], v[146:149], v[184:187], v[72:75]
	v_mfma_f32_16x16x32_bf16 v[60:63], v[128:131], v[192:195], v[60:63]
	v_mfma_f32_16x16x32_bf16 v[56:59], v[146:149], v[192:195], v[56:59]
	v_mfma_f32_16x16x32_bf16 v[92:95], v[132:135], v[172:175], v[92:95]
	v_mfma_f32_16x16x32_bf16 v[88:91], v[150:153], v[172:175], v[88:91]
	v_mfma_f32_16x16x32_bf16 v[84:87], v[132:135], v[180:183], v[84:87]
	v_mfma_f32_16x16x32_bf16 v[80:83], v[150:153], v[180:183], v[80:83]
	v_mfma_f32_16x16x32_bf16 v[76:79], v[132:135], v[188:191], v[76:79]
	v_mfma_f32_16x16x32_bf16 v[72:75], v[150:153], v[188:191], v[72:75]
	v_mfma_f32_16x16x32_bf16 v[60:63], v[132:135], v[196:199], v[60:63]
	v_mfma_f32_16x16x32_bf16 v[56:59], v[150:153], v[196:199], v[56:59]
	s_setprio 0
	s_barrier
	s_add_u32 s8, s62, 0x40080
	s_addc_u32 s9, s63, 0
	s_add_i32 s16, s17, s37
	v_lshl_add_u64 v[128:129], s[8:9], 0, v[160:161]
	s_mov_b32 m0, s16
	s_nop 0
	global_load_lds_dwordx4 v[128:129], off
	v_lshl_add_u64 v[128:129], s[8:9], 0, v[136:137]
	s_add_i32 m0, s16, 0x2000
	s_nop 0
	global_load_lds_dwordx4 v[128:129], off
	s_waitcnt vmcnt(6)
	s_barrier
	s_setprio 1
	v_mfma_f32_16x16x32_bf16 v[28:31], v[200:203], v[154:157], v[28:31]
	v_mfma_f32_16x16x32_bf16 v[24:27], v[208:211], v[154:157], v[24:27]
	v_mfma_f32_16x16x32_bf16 v[20:23], v[200:203], v[176:179], v[20:23]
	v_mfma_f32_16x16x32_bf16 v[16:19], v[208:211], v[176:179], v[16:19]
	v_mfma_f32_16x16x32_bf16 v[12:15], v[200:203], v[184:187], v[12:15]
	v_mfma_f32_16x16x32_bf16 v[8:11], v[208:211], v[184:187], v[8:11]
	v_mfma_f32_16x16x32_bf16 v[4:7], v[200:203], v[192:195], v[4:7]
	v_mfma_f32_16x16x32_bf16 v[0:3], v[208:211], v[192:195], v[0:3]
	v_mfma_f32_16x16x32_bf16 v[28:31], v[204:207], v[172:175], v[28:31]
	v_mfma_f32_16x16x32_bf16 v[24:27], v[212:215], v[172:175], v[24:27]
	v_mfma_f32_16x16x32_bf16 v[20:23], v[204:207], v[180:183], v[20:23]
	v_mfma_f32_16x16x32_bf16 v[16:19], v[212:215], v[180:183], v[16:19]
	v_mfma_f32_16x16x32_bf16 v[12:15], v[204:207], v[188:191], v[12:15]
	v_mfma_f32_16x16x32_bf16 v[8:11], v[212:215], v[188:191], v[8:11]
	v_mfma_f32_16x16x32_bf16 v[4:7], v[204:207], v[196:199], v[4:7]
	v_mfma_f32_16x16x32_bf16 v[0:3], v[212:215], v[196:199], v[0:3]
	s_setprio 0
	s_add_i32 s15, s15, 2
	s_add_u32 s60, s60, 0x100
	s_addc_u32 s61, s61, 0
	s_add_u32 s13, s13, 0x100
	s_addc_u32 s14, s14, 0
	s_cmp_gt_u32 s15, 13
	s_barrier
	s_cbranch_scc0 .LBB0_350
	v_lshl_add_u32 v146, s65, 8, v159
	v_readlane_b32 s8, v249, 24
	v_ashrrev_i32_e32 v147, 31, v146
	v_readlane_b32 s9, v249, 25
	v_readlane_b32 s12, v249, 26
	v_lshl_or_b32 v156, s66, 8, v169
	v_lshl_add_u64 v[128:129], v[146:147], 3, s[8:9]
	s_ashr_i32 s8, s65, 5
	s_ashr_i32 s9, s8, 31
	s_lshl_b64 s[8:9], s[8:9], 14
	v_readlane_b32 s13, v249, 27
	s_add_u32 s8, s12, s8
	v_ashrrev_i32_e32 v157, 31, v156
	s_addc_u32 s9, s13, s9
	v_lshl_add_u64 v[180:181], v[156:157], 2, s[8:9]
	v_readlane_b32 s8, v253, 29
	v_readlane_b32 s9, v253, 30
	s_mov_b32 s1, 0x100000
	s_mov_b32 s66, s0
	s_mov_b32 s65, s4
	s_mov_b64 s[20:21], s[6:7]
	v_readlane_b32 s62, v255, 4
	v_readlane_b32 s63, v255, 5
	s_waitcnt vmcnt(0)
	v_mov_b32_e32 v130, v242
	v_mov_b32_e32 v131, v243
	v_mov_b32_e32 v218, v244
	v_mov_b32_e32 v219, v245
	v_mov_b32_e32 v220, v164
	v_mov_b32_e32 v221, v165
	v_mov_b32_e32 v222, v166
	v_mov_b32_e32 v223, v167
	v_ffbh_u32_e32 v132, v131
	v_min_u32_e32 v132, 32, v132
	v_lshlrev_b64 v[130:131], v132, v[130:131]
	v_min_u32_e32 v130, 1, v130
	v_or_b32_e32 v130, v131, v130
	v_cvt_f32_u32_e32 v130, v130
	v_sub_u32_e32 v131, 32, v132
	v_ldexp_f32 v130, v130, v131
	v_mul_f32_e32 v130, 0x37800000, v130
	v_fmamk_f32 v158, v130, 0x3a800000, v240
	v_mov_b32_e32 v130, v218
	v_mov_b32_e32 v131, v219
	v_cmp_gt_f32_e32 vcc, s53, v158
	v_mul_f32_e32 v164, 0x4b800000, v158
	v_ffbh_u32_e32 v132, v131
	v_min_u32_e32 v132, 32, v132
	v_lshlrev_b64 v[130:131], v132, v[130:131]
	v_min_u32_e32 v130, 1, v130
	v_or_b32_e32 v130, v131, v130
	v_cvt_f32_u32_e32 v130, v130
	v_sub_u32_e32 v131, 32, v132
	v_cndmask_b32_e32 v158, v158, v164, vcc
	v_rsq_f32_e32 v158, v158
	v_ldexp_f32 v130, v130, v131
	v_mul_f32_e32 v130, 0x37800000, v130
	v_fmamk_f32 v171, v130, 0x3a800000, v240
	v_mov_b32_e32 v130, v220
	v_mov_b32_e32 v131, v221
	v_mul_f32_e32 v164, 0x45800000, v158
	v_cndmask_b32_e32 v184, v158, v164, vcc
	v_cmp_gt_f32_e32 vcc, s53, v171
	v_mul_f32_e32 v158, 0x4b800000, v171
	v_ffbh_u32_e32 v132, v131
	v_min_u32_e32 v132, 32, v132
	v_lshlrev_b64 v[130:131], v132, v[130:131]
	v_min_u32_e32 v130, 1, v130
	v_or_b32_e32 v130, v131, v130
	v_cvt_f32_u32_e32 v130, v130
	v_sub_u32_e32 v131, 32, v132
	v_cndmask_b32_e32 v158, v171, v158, vcc
	v_rsq_f32_e32 v158, v158
	v_ldexp_f32 v130, v130, v131
	v_mul_f32_e32 v130, 0x37800000, v130
	v_fmamk_f32 v172, v130, 0x3a800000, v240
	v_mov_b32_e32 v130, v222
	v_mov_b32_e32 v131, v223
	v_mul_f32_e32 v164, 0x45800000, v158
	v_cndmask_b32_e32 v182, v158, v164, vcc
	v_cmp_gt_f32_e32 vcc, s53, v172
	v_mul_f32_e32 v158, 0x4b800000, v172
	v_ffbh_u32_e32 v132, v131
	v_min_u32_e32 v132, 32, v132
	v_lshlrev_b64 v[130:131], v132, v[130:131]
	v_min_u32_e32 v130, 1, v130
	v_or_b32_e32 v130, v131, v130
	v_cvt_f32_u32_e32 v130, v130
	v_sub_u32_e32 v131, 32, v132
	v_cndmask_b32_e32 v158, v172, v158, vcc
	v_rsq_f32_e32 v158, v158
	v_ldexp_f32 v130, v130, v131
	v_mul_f32_e32 v130, 0x37800000, v130
	v_fmamk_f32 v173, v130, 0x3a800000, v240
	v_mov_b32_e32 v130, v224
	v_mov_b32_e32 v131, v225
	v_mul_f32_e32 v164, 0x45800000, v158
	v_ffbh_u32_e32 v132, v131
	v_min_u32_e32 v132, 32, v132
	v_lshlrev_b64 v[130:131], v132, v[130:131]
	v_min_u32_e32 v130, 1, v130
	v_or_b32_e32 v130, v131, v130
	v_cvt_f32_u32_e32 v130, v130
	v_sub_u32_e32 v131, 32, v132
	v_ldexp_f32 v130, v130, v131
	v_mul_f32_e32 v130, 0x37800000, v130
	v_fmamk_f32 v174, v130, 0x3a800000, v240
	v_mov_b32_e32 v130, v226
	v_mov_b32_e32 v131, v227
	v_ffbh_u32_e32 v132, v131
	v_min_u32_e32 v132, 32, v132
	v_lshlrev_b64 v[130:131], v132, v[130:131]
	v_min_u32_e32 v130, 1, v130
	v_or_b32_e32 v130, v131, v130
	v_cvt_f32_u32_e32 v130, v130
	v_sub_u32_e32 v131, 32, v132
	v_ldexp_f32 v130, v130, v131
	v_mul_f32_e32 v130, 0x37800000, v130
	v_fmamk_f32 v175, v130, 0x3a800000, v240
	v_mov_b32_e32 v130, v228
	v_mov_b32_e32 v131, v229
	v_ffbh_u32_e32 v132, v131
	v_mov_b32_e32 v128, v230
	v_mov_b32_e32 v129, v231
	v_min_u32_e32 v132, 32, v132
	v_lshlrev_b64 v[130:131], v132, v[130:131]
	v_min_u32_e32 v130, 1, v130
	v_or_b32_e32 v130, v131, v130
	v_cvt_f32_u32_e32 v130, v130
	v_sub_u32_e32 v131, 32, v132
	v_ldexp_f32 v130, v130, v131
	v_mul_f32_e32 v130, 0x37800000, v130
	v_fmamk_f32 v177, v130, 0x3a800000, v240
	v_ffbh_u32_e32 v130, v129
	v_min_u32_e32 v130, 32, v130
	v_lshlrev_b64 v[128:129], v130, v[128:129]
	v_min_u32_e32 v128, 1, v128
	v_or_b32_e32 v128, v129, v128
	v_cvt_f32_u32_e32 v128, v128
	v_sub_u32_e32 v129, 32, v130
	v_ldexp_f32 v128, v128, v129
	v_mul_f32_e32 v128, 0x37800000, v128
	v_fmamk_f32 v179, v128, 0x3a800000, v240
	v_mov_b32_e32 v128, v232
	v_mov_b32_e32 v129, v233
	v_mov_b32_e32 v130, v234
	v_mov_b32_e32 v131, v235
	v_mov_b32_e32 v132, v236
	v_mov_b32_e32 v133, v237
	v_mov_b32_e32 v134, v238
	v_mov_b32_e32 v135, v239
	s_waitcnt vmcnt(0)
	v_pk_add_f32 v[148:149], v[130:131], 0 op_sel_hi:[1,0]
	v_pk_add_f32 v[152:153], v[134:135], 0 op_sel_hi:[1,0]
	v_pk_add_f32 v[154:155], v[132:133], 0 op_sel_hi:[1,0]
	v_pk_add_f32 v[150:151], v[128:129], 0 op_sel_hi:[1,0]
	global_load_dwordx4 v[128:131], v[180:181], off offset:528
	global_load_dwordx4 v[132:135], v[180:181], off offset:512
	v_cndmask_b32_e32 v180, v158, v164, vcc
	v_cmp_gt_f32_e32 vcc, s53, v173
	v_mul_f32_e32 v158, 0x4b800000, v173
	v_pk_fma_f32 v[122:123], v[122:123], v[184:185], v[148:149] op_sel_hi:[1,0,1]
	v_cndmask_b32_e32 v158, v173, v158, vcc
	v_rsq_f32_e32 v158, v158
	v_pk_fma_f32 v[126:127], v[126:127], v[184:185], v[152:153] op_sel_hi:[1,0,1]
	v_pk_fma_f32 v[124:125], v[124:125], v[184:185], v[154:155] op_sel_hi:[1,0,1]
	v_pk_fma_f32 v[120:121], v[120:121], v[184:185], v[150:151] op_sel_hi:[1,0,1]
	v_mul_f32_e32 v164, 0x45800000, v158
	v_cndmask_b32_e32 v178, v158, v164, vcc
	v_cmp_gt_f32_e32 vcc, s53, v174
	v_mul_f32_e32 v158, 0x4b800000, v174
	v_max_f32_e32 v122, 0, v122
	v_cndmask_b32_e32 v158, v174, v158, vcc
	v_rsq_f32_e32 v158, v158
	v_max_f32_e32 v124, 0, v124
	v_max_f32_e32 v120, 0, v120
	v_max_f32_e32 v121, 0, v121
	v_mul_f32_e32 v164, 0x45800000, v158
	v_cndmask_b32_e32 v176, v158, v164, vcc
	v_cmp_gt_f32_e32 vcc, s53, v175
	v_mul_f32_e32 v158, 0x4b800000, v175
	v_mul_f32_e32 v124, v124, v124
	v_cndmask_b32_e32 v158, v175, v158, vcc
	v_rsq_f32_e32 v158, v158
	v_mul_f32_e32 v120, v120, v120
	v_max_f32_e32 v125, 0, v125
	v_mul_f32_e32 v121, v121, v121
	v_mul_f32_e32 v164, 0x45800000, v158
	v_cndmask_b32_e32 v174, v158, v164, vcc
	v_cmp_gt_f32_e32 vcc, s53, v177
	v_mul_f32_e32 v158, 0x4b800000, v177
	v_max_f32_e32 v126, 0, v126
	v_cndmask_b32_e32 v158, v177, v158, vcc
	v_rsq_f32_e32 v158, v158
	v_mul_f32_e32 v125, v125, v125
	v_mul_f32_e32 v126, v126, v126
	v_pk_fma_f32 v[114:115], v[114:115], v[182:183], v[148:149] op_sel_hi:[1,0,1]
	v_mul_f32_e32 v164, 0x45800000, v158
	v_cndmask_b32_e32 v172, v158, v164, vcc
	v_cmp_gt_f32_e32 vcc, s53, v179
	v_mul_f32_e32 v158, 0x4b800000, v179
	v_pk_fma_f32 v[118:119], v[118:119], v[182:183], v[152:153] op_sel_hi:[1,0,1]
	v_cndmask_b32_e32 v158, v179, v158, vcc
	v_rsq_f32_e32 v158, v158
	v_pk_fma_f32 v[116:117], v[116:117], v[182:183], v[154:155] op_sel_hi:[1,0,1]
	v_pk_fma_f32 v[112:113], v[112:113], v[182:183], v[150:151] op_sel_hi:[1,0,1]
	v_max_f32_e32 v114, 0, v114
	v_mul_f32_e32 v164, 0x45800000, v158
	v_cndmask_b32_e32 v158, v158, v164, vcc
	v_mul_f32_e32 v164, v122, v122
	v_max_f32_e32 v122, 0, v127
	v_mul_f32_e32 v127, v122, v122
	v_max_f32_e32 v122, 0, v123
	v_mul_f32_e32 v165, v122, v122
	v_cvt_pk_bf16_f32 v122, v124, v125
	v_cvt_pk_bf16_f32 v123, v126, v127
	v_cvt_pk_bf16_f32 v124, v120, v121
	v_lshlrev_b64 v[120:121], 13, v[146:147]
	v_lshl_add_u64 v[120:121], s[8:9], 0, v[120:121]
	v_lshlrev_b64 v[126:127], 1, v[156:157]
	v_lshl_add_u64 v[120:121], v[120:121], 0, v[126:127]
	v_cvt_pk_bf16_f32 v125, v164, v165
	global_store_dwordx4 v[120:121], v[122:125], off
	v_max_f32_e32 v116, 0, v116
	v_max_f32_e32 v112, 0, v112
	v_mul_f32_e32 v122, v114, v114
	v_max_f32_e32 v114, 0, v119
	v_mul_f32_e32 v116, v116, v116
	v_mul_f32_e32 v112, v112, v112
	v_max_f32_e32 v117, 0, v117
	v_max_f32_e32 v113, 0, v113
	v_max_f32_e32 v118, 0, v118
	v_mul_f32_e32 v119, v114, v114
	v_max_f32_e32 v114, 0, v115
	v_mul_f32_e32 v117, v117, v117
	v_mul_f32_e32 v113, v113, v113
	v_mul_f32_e32 v118, v118, v118
	v_mul_f32_e32 v123, v114, v114
	v_cvt_pk_bf16_f32 v114, v116, v117
	v_cvt_pk_bf16_f32 v115, v118, v119
	v_cvt_pk_bf16_f32 v116, v112, v113
	v_or_b32_e32 v112, 16, v146
	v_ashrrev_i32_e32 v113, 31, v112
	v_lshlrev_b64 v[112:113], 13, v[112:113]
	v_lshl_add_u64 v[112:113], s[8:9], 0, v[112:113]
	v_pk_fma_f32 v[106:107], v[106:107], v[180:181], v[148:149] op_sel_hi:[1,0,1]
	v_lshl_add_u64 v[112:113], v[112:113], 0, v[126:127]
	v_pk_fma_f32 v[110:111], v[110:111], v[180:181], v[152:153] op_sel_hi:[1,0,1]
	v_pk_fma_f32 v[108:109], v[108:109], v[180:181], v[154:155] op_sel_hi:[1,0,1]
	v_pk_fma_f32 v[104:105], v[104:105], v[180:181], v[150:151] op_sel_hi:[1,0,1]
	v_max_f32_e32 v106, 0, v106
	v_cvt_pk_bf16_f32 v117, v122, v123
	global_store_dwordx4 v[112:113], v[114:117], off
	v_max_f32_e32 v108, 0, v108
	v_max_f32_e32 v104, 0, v104
	v_mul_f32_e32 v114, v106, v106
	v_max_f32_e32 v106, 0, v111
	v_mul_f32_e32 v108, v108, v108
	v_mul_f32_e32 v104, v104, v104
	v_max_f32_e32 v109, 0, v109
	v_max_f32_e32 v105, 0, v105
	v_max_f32_e32 v110, 0, v110
	v_mul_f32_e32 v111, v106, v106
	v_max_f32_e32 v106, 0, v107
	v_mul_f32_e32 v109, v109, v109
	v_mul_f32_e32 v105, v105, v105
	v_mul_f32_e32 v110, v110, v110
	v_mul_f32_e32 v115, v106, v106
	v_cvt_pk_bf16_f32 v106, v108, v109
	v_cvt_pk_bf16_f32 v107, v110, v111
	v_cvt_pk_bf16_f32 v108, v104, v105
	v_or_b32_e32 v104, 32, v146
	v_ashrrev_i32_e32 v105, 31, v104
	v_lshlrev_b64 v[104:105], 13, v[104:105]
	v_lshl_add_u64 v[104:105], s[8:9], 0, v[104:105]
	v_pk_fma_f32 v[98:99], v[98:99], v[178:179], v[148:149] op_sel_hi:[1,0,1]
	v_lshl_add_u64 v[104:105], v[104:105], 0, v[126:127]
	v_pk_fma_f32 v[102:103], v[102:103], v[178:179], v[152:153] op_sel_hi:[1,0,1]
	v_pk_fma_f32 v[100:101], v[100:101], v[178:179], v[154:155] op_sel_hi:[1,0,1]
	v_pk_fma_f32 v[96:97], v[96:97], v[178:179], v[150:151] op_sel_hi:[1,0,1]
	v_max_f32_e32 v98, 0, v98
	v_cvt_pk_bf16_f32 v109, v114, v115
	global_store_dwordx4 v[104:105], v[106:109], off
	v_max_f32_e32 v100, 0, v100
	v_max_f32_e32 v96, 0, v96
	v_mul_f32_e32 v106, v98, v98
	v_max_f32_e32 v98, 0, v103
	v_mul_f32_e32 v100, v100, v100
	v_mul_f32_e32 v96, v96, v96
	v_max_f32_e32 v101, 0, v101
	v_max_f32_e32 v97, 0, v97
	v_max_f32_e32 v102, 0, v102
	v_mul_f32_e32 v103, v98, v98
	v_max_f32_e32 v98, 0, v99
	v_mul_f32_e32 v101, v101, v101
	v_mul_f32_e32 v97, v97, v97
	v_mul_f32_e32 v102, v102, v102
	v_mul_f32_e32 v107, v98, v98
	v_cvt_pk_bf16_f32 v98, v100, v101
	v_cvt_pk_bf16_f32 v99, v102, v103
	v_cvt_pk_bf16_f32 v100, v96, v97
	v_or_b32_e32 v96, 48, v146
	v_ashrrev_i32_e32 v97, 31, v96
	v_lshlrev_b64 v[96:97], 13, v[96:97]
	v_lshl_add_u64 v[96:97], s[8:9], 0, v[96:97]
	v_pk_fma_f32 v[90:91], v[90:91], v[176:177], v[148:149] op_sel_hi:[1,0,1]
	v_lshl_add_u64 v[96:97], v[96:97], 0, v[126:127]
	v_pk_fma_f32 v[94:95], v[94:95], v[176:177], v[152:153] op_sel_hi:[1,0,1]
	v_max_f32_e32 v90, 0, v90
	v_cvt_pk_bf16_f32 v101, v106, v107
	global_store_dwordx4 v[96:97], v[98:101], off
	v_pk_fma_f32 v[92:93], v[92:93], v[176:177], v[154:155] op_sel_hi:[1,0,1]
	v_max_f32_e32 v94, 0, v94
	v_mul_f32_e32 v98, v90, v90
	v_max_f32_e32 v90, 0, v95
	v_max_f32_e32 v92, 0, v92
	v_max_f32_e32 v93, 0, v93
	v_mul_f32_e32 v94, v94, v94
	v_mul_f32_e32 v95, v90, v90
	v_max_f32_e32 v90, 0, v91
	v_pk_fma_f32 v[88:89], v[88:89], v[176:177], v[150:151] op_sel_hi:[1,0,1]
	v_mul_f32_e32 v92, v92, v92
	v_mul_f32_e32 v93, v93, v93
	v_mul_f32_e32 v99, v90, v90
	v_cvt_pk_bf16_f32 v90, v92, v93
	v_cvt_pk_bf16_f32 v91, v94, v95
	v_add_co_u32_e32 v94, vcc, s1, v120
	v_pk_fma_f32 v[82:83], v[82:83], v[174:175], v[148:149] op_sel_hi:[1,0,1]
	v_max_f32_e32 v88, 0, v88
	v_max_f32_e32 v89, 0, v89
	v_addc_co_u32_e32 v95, vcc, 0, v121, vcc
	v_pk_fma_f32 v[86:87], v[86:87], v[174:175], v[152:153] op_sel_hi:[1,0,1]
	v_max_f32_e32 v82, 0, v82
	v_mul_f32_e32 v88, v88, v88
	v_mul_f32_e32 v89, v89, v89
	v_cvt_pk_bf16_f32 v92, v88, v89
	v_cvt_pk_bf16_f32 v93, v98, v99
	global_store_dwordx4 v[94:95], v[90:93], off
	v_pk_fma_f32 v[84:85], v[84:85], v[174:175], v[154:155] op_sel_hi:[1,0,1]
	v_max_f32_e32 v86, 0, v86
	v_mul_f32_e32 v90, v82, v82
	v_max_f32_e32 v82, 0, v87
	v_max_f32_e32 v84, 0, v84
	v_max_f32_e32 v85, 0, v85
	v_mul_f32_e32 v86, v86, v86
	v_mul_f32_e32 v87, v82, v82
	v_max_f32_e32 v82, 0, v83
	s_mov_b32 s1, 0x120000
	v_pk_fma_f32 v[80:81], v[80:81], v[174:175], v[150:151] op_sel_hi:[1,0,1]
	v_mul_f32_e32 v84, v84, v84
	v_mul_f32_e32 v85, v85, v85
	v_mul_f32_e32 v91, v82, v82
	v_cvt_pk_bf16_f32 v82, v84, v85
	v_cvt_pk_bf16_f32 v83, v86, v87
	v_add_co_u32_e32 v86, vcc, s1, v120
	v_pk_fma_f32 v[74:75], v[74:75], v[172:173], v[148:149] op_sel_hi:[1,0,1]
	v_max_f32_e32 v80, 0, v80
	v_max_f32_e32 v81, 0, v81
	v_addc_co_u32_e32 v87, vcc, 0, v121, vcc
	v_pk_fma_f32 v[78:79], v[78:79], v[172:173], v[152:153] op_sel_hi:[1,0,1]
	v_max_f32_e32 v74, 0, v74
	v_mul_f32_e32 v80, v80, v80
	v_mul_f32_e32 v81, v81, v81
	v_cvt_pk_bf16_f32 v84, v80, v81
	v_cvt_pk_bf16_f32 v85, v90, v91
	global_store_dwordx4 v[86:87], v[82:85], off
	v_pk_fma_f32 v[76:77], v[76:77], v[172:173], v[154:155] op_sel_hi:[1,0,1]
	v_max_f32_e32 v78, 0, v78
	v_mul_f32_e32 v82, v74, v74
	v_max_f32_e32 v74, 0, v79
	v_max_f32_e32 v76, 0, v76
	v_max_f32_e32 v77, 0, v77
	v_mul_f32_e32 v78, v78, v78
	v_mul_f32_e32 v79, v74, v74
	v_max_f32_e32 v74, 0, v75
	s_mov_b32 s1, 0x140000
	v_pk_fma_f32 v[72:73], v[72:73], v[172:173], v[150:151] op_sel_hi:[1,0,1]
	v_mul_f32_e32 v76, v76, v76
	v_mul_f32_e32 v77, v77, v77
	v_mul_f32_e32 v83, v74, v74
	v_cvt_pk_bf16_f32 v74, v76, v77
	v_cvt_pk_bf16_f32 v75, v78, v79
	v_add_co_u32_e32 v78, vcc, s1, v120
	v_pk_fma_f32 v[58:59], v[58:59], v[158:159], v[148:149] op_sel_hi:[1,0,1]
	v_max_f32_e32 v72, 0, v72
	v_max_f32_e32 v73, 0, v73
	v_addc_co_u32_e32 v79, vcc, 0, v121, vcc
	v_pk_fma_f32 v[62:63], v[62:63], v[158:159], v[152:153] op_sel_hi:[1,0,1]
	v_max_f32_e32 v58, 0, v58
	v_mul_f32_e32 v72, v72, v72
	v_mul_f32_e32 v73, v73, v73
	v_cvt_pk_bf16_f32 v76, v72, v73
	v_cvt_pk_bf16_f32 v77, v82, v83
	global_store_dwordx4 v[78:79], v[74:77], off
	v_pk_fma_f32 v[60:61], v[60:61], v[158:159], v[154:155] op_sel_hi:[1,0,1]
	v_max_f32_e32 v62, 0, v62
	v_mul_f32_e32 v74, v58, v58
	v_max_f32_e32 v58, 0, v63
	v_max_f32_e32 v60, 0, v60
	v_max_f32_e32 v61, 0, v61
	v_mul_f32_e32 v62, v62, v62
	v_mul_f32_e32 v63, v58, v58
	v_max_f32_e32 v58, 0, v59
	s_mov_b32 s1, 0x160000
	v_pk_fma_f32 v[56:57], v[56:57], v[158:159], v[150:151] op_sel_hi:[1,0,1]
	v_mul_f32_e32 v60, v60, v60
	v_mul_f32_e32 v61, v61, v61
	v_mul_f32_e32 v75, v58, v58
	v_cvt_pk_bf16_f32 v58, v60, v61
	v_cvt_pk_bf16_f32 v59, v62, v63
	v_add_co_u32_e32 v62, vcc, s1, v120
	s_waitcnt vmcnt(7)
	v_pk_add_f32 v[134:135], v[134:135], 0 op_sel_hi:[1,0]
	v_max_f32_e32 v56, 0, v56
	v_max_f32_e32 v57, 0, v57
	v_addc_co_u32_e32 v63, vcc, 0, v121, vcc
	v_pk_add_f32 v[130:131], v[130:131], 0 op_sel_hi:[1,0]
	v_mul_f32_e32 v56, v56, v56
	v_mul_f32_e32 v57, v57, v57
	v_cvt_pk_bf16_f32 v60, v56, v57
	v_cvt_pk_bf16_f32 v61, v74, v75
	global_store_dwordx4 v[62:63], v[58:61], off
	v_pk_fma_f32 v[62:63], v[66:67], v[184:185], v[130:131] op_sel_hi:[1,0,1]
	v_pk_add_f32 v[132:133], v[132:133], 0 op_sel_hi:[1,0]
	v_pk_fma_f32 v[58:59], v[70:71], v[184:185], v[134:135] op_sel_hi:[1,0,1]
	v_pk_add_f32 v[128:129], v[128:129], 0 op_sel_hi:[1,0]
	v_max_f32_e32 v58, 0, v58
	v_mul_f32_e32 v66, v58, v58
	v_max_f32_e32 v58, 0, v62
	v_pk_fma_f32 v[60:61], v[68:69], v[184:185], v[132:133] op_sel_hi:[1,0,1]
	v_mul_f32_e32 v62, v58, v58
	v_max_f32_e32 v58, 0, v59
	v_pk_fma_f32 v[64:65], v[64:65], v[184:185], v[128:129] op_sel_hi:[1,0,1]
	v_max_f32_e32 v60, 0, v60
	v_max_f32_e32 v61, 0, v61
	v_mul_f32_e32 v59, v58, v58
	v_max_f32_e32 v58, 0, v63
	v_pk_fma_f32 v[48:49], v[48:49], v[182:183], v[128:129] op_sel_hi:[1,0,1]
	v_mul_f32_e32 v60, v60, v60
	v_max_f32_e32 v64, 0, v64
	v_mul_f32_e32 v61, v61, v61
	v_max_f32_e32 v65, 0, v65
	v_mul_f32_e32 v63, v58, v58
	v_cvt_pk_bf16_f32 v58, v60, v61
	v_pk_fma_f32 v[52:53], v[52:53], v[182:183], v[132:133] op_sel_hi:[1,0,1]
	v_pk_fma_f32 v[50:51], v[50:51], v[182:183], v[130:131] op_sel_hi:[1,0,1]
	v_max_f32_e32 v48, 0, v48
	v_mul_f32_e32 v64, v64, v64
	v_mul_f32_e32 v65, v65, v65
	v_cvt_pk_bf16_f32 v59, v66, v59
	v_cvt_pk_bf16_f32 v60, v64, v65
	v_cvt_pk_bf16_f32 v61, v62, v63
	global_store_dwordx4 v[120:121], v[58:61], off offset:256
	v_pk_fma_f32 v[54:55], v[54:55], v[182:183], v[134:135] op_sel_hi:[1,0,1]
	v_max_f32_e32 v49, 0, v49
	v_mul_f32_e32 v58, v48, v48
	v_max_f32_e32 v48, 0, v53
	v_max_f32_e32 v50, 0, v50
	v_max_f32_e32 v52, 0, v52
	v_mul_f32_e32 v48, v48, v48
	v_mul_f32_e32 v53, v49, v49
	v_max_f32_e32 v49, 0, v54
	v_mul_f32_e32 v54, v50, v50
	v_max_f32_e32 v50, 0, v55
	v_max_f32_e32 v51, 0, v51
	v_pk_fma_f32 v[40:41], v[40:41], v[180:181], v[128:129] op_sel_hi:[1,0,1]
	v_mul_f32_e32 v52, v52, v52
	v_mul_f32_e32 v49, v49, v49
	v_mul_f32_e32 v50, v50, v50
	v_mul_f32_e32 v51, v51, v51
	v_cvt_pk_bf16_f32 v48, v52, v48
	v_pk_fma_f32 v[44:45], v[44:45], v[180:181], v[132:133] op_sel_hi:[1,0,1]
	v_pk_fma_f32 v[42:43], v[42:43], v[180:181], v[130:131] op_sel_hi:[1,0,1]
	v_max_f32_e32 v40, 0, v40
	v_cvt_pk_bf16_f32 v49, v49, v50
	v_cvt_pk_bf16_f32 v50, v58, v53
	v_cvt_pk_bf16_f32 v51, v54, v51
	global_store_dwordx4 v[112:113], v[48:51], off offset:256
	v_pk_fma_f32 v[46:47], v[46:47], v[180:181], v[134:135] op_sel_hi:[1,0,1]
	v_max_f32_e32 v41, 0, v41
	v_mul_f32_e32 v48, v40, v40
	v_max_f32_e32 v40, 0, v45
	v_max_f32_e32 v42, 0, v42
	v_max_f32_e32 v44, 0, v44
	v_mul_f32_e32 v40, v40, v40
	v_mul_f32_e32 v45, v41, v41
	v_max_f32_e32 v41, 0, v46
	v_mul_f32_e32 v46, v42, v42
	v_max_f32_e32 v42, 0, v47
	v_max_f32_e32 v43, 0, v43
	v_pk_fma_f32 v[32:33], v[32:33], v[178:179], v[128:129] op_sel_hi:[1,0,1]
	v_mul_f32_e32 v44, v44, v44
	v_mul_f32_e32 v41, v41, v41
	v_mul_f32_e32 v42, v42, v42
	v_mul_f32_e32 v43, v43, v43
	v_cvt_pk_bf16_f32 v40, v44, v40
	v_pk_fma_f32 v[36:37], v[36:37], v[178:179], v[132:133] op_sel_hi:[1,0,1]
	v_pk_fma_f32 v[34:35], v[34:35], v[178:179], v[130:131] op_sel_hi:[1,0,1]
	v_max_f32_e32 v32, 0, v32
	v_cvt_pk_bf16_f32 v41, v41, v42
	v_cvt_pk_bf16_f32 v42, v48, v45
	v_cvt_pk_bf16_f32 v43, v46, v43
	global_store_dwordx4 v[104:105], v[40:43], off offset:256
	v_pk_fma_f32 v[38:39], v[38:39], v[178:179], v[134:135] op_sel_hi:[1,0,1]
	v_max_f32_e32 v33, 0, v33
	v_mul_f32_e32 v40, v32, v32
	v_max_f32_e32 v32, 0, v37
	v_max_f32_e32 v34, 0, v34
	v_max_f32_e32 v36, 0, v36
	v_mul_f32_e32 v32, v32, v32
	v_mul_f32_e32 v37, v33, v33
	v_max_f32_e32 v33, 0, v38
	v_mul_f32_e32 v38, v34, v34
	v_max_f32_e32 v34, 0, v39
	v_max_f32_e32 v35, 0, v35
	v_pk_fma_f32 v[24:25], v[24:25], v[176:177], v[128:129] op_sel_hi:[1,0,1]
	v_mul_f32_e32 v36, v36, v36
	v_mul_f32_e32 v33, v33, v33
	v_mul_f32_e32 v34, v34, v34
	v_mul_f32_e32 v35, v35, v35
	v_cvt_pk_bf16_f32 v32, v36, v32
	v_pk_fma_f32 v[28:29], v[28:29], v[176:177], v[132:133] op_sel_hi:[1,0,1]
	v_pk_fma_f32 v[26:27], v[26:27], v[176:177], v[130:131] op_sel_hi:[1,0,1]
	v_max_f32_e32 v24, 0, v24
	v_cvt_pk_bf16_f32 v33, v33, v34
	v_cvt_pk_bf16_f32 v34, v40, v37
	v_cvt_pk_bf16_f32 v35, v38, v35
	global_store_dwordx4 v[96:97], v[32:35], off offset:256
	v_pk_fma_f32 v[30:31], v[30:31], v[176:177], v[134:135] op_sel_hi:[1,0,1]
	v_max_f32_e32 v25, 0, v25
	v_mul_f32_e32 v32, v24, v24
	v_max_f32_e32 v24, 0, v29
	v_max_f32_e32 v26, 0, v26
	s_mov_b64 s[8:9], 0x100000
	v_max_f32_e32 v28, 0, v28
	v_mul_f32_e32 v24, v24, v24
	v_mul_f32_e32 v29, v25, v25
	v_max_f32_e32 v25, 0, v30
	v_mul_f32_e32 v30, v26, v26
	v_max_f32_e32 v26, 0, v31
	v_max_f32_e32 v27, 0, v27
	v_pk_fma_f32 v[16:17], v[16:17], v[174:175], v[128:129] op_sel_hi:[1,0,1]
	v_lshl_add_u64 v[88:89], v[120:121], 0, s[8:9]
	v_mul_f32_e32 v28, v28, v28
	v_mul_f32_e32 v25, v25, v25
	v_mul_f32_e32 v26, v26, v26
	v_mul_f32_e32 v27, v27, v27
	v_cvt_pk_bf16_f32 v24, v28, v24
	v_pk_fma_f32 v[20:21], v[20:21], v[174:175], v[132:133] op_sel_hi:[1,0,1]
	v_pk_fma_f32 v[18:19], v[18:19], v[174:175], v[130:131] op_sel_hi:[1,0,1]
	v_max_f32_e32 v16, 0, v16
	v_cvt_pk_bf16_f32 v25, v25, v26
	v_cvt_pk_bf16_f32 v26, v32, v29
	v_cvt_pk_bf16_f32 v27, v30, v27
	global_store_dwordx4 v[88:89], v[24:27], off offset:256
	v_pk_fma_f32 v[22:23], v[22:23], v[174:175], v[134:135] op_sel_hi:[1,0,1]
	v_max_f32_e32 v17, 0, v17
	v_mul_f32_e32 v24, v16, v16
	v_max_f32_e32 v16, 0, v21
	v_max_f32_e32 v18, 0, v18
	s_mov_b64 s[8:9], 0x120000
	v_max_f32_e32 v20, 0, v20
	v_mul_f32_e32 v16, v16, v16
	v_mul_f32_e32 v21, v17, v17
	v_max_f32_e32 v17, 0, v22
	v_mul_f32_e32 v22, v18, v18
	v_max_f32_e32 v18, 0, v23
	v_max_f32_e32 v19, 0, v19
	v_pk_fma_f32 v[8:9], v[8:9], v[172:173], v[128:129] op_sel_hi:[1,0,1]
	v_lshl_add_u64 v[80:81], v[120:121], 0, s[8:9]
	v_mul_f32_e32 v20, v20, v20
	v_mul_f32_e32 v17, v17, v17
	v_mul_f32_e32 v18, v18, v18
	v_mul_f32_e32 v19, v19, v19
	v_cvt_pk_bf16_f32 v16, v20, v16
	v_pk_fma_f32 v[12:13], v[12:13], v[172:173], v[132:133] op_sel_hi:[1,0,1]
	v_pk_fma_f32 v[10:11], v[10:11], v[172:173], v[130:131] op_sel_hi:[1,0,1]
	v_max_f32_e32 v8, 0, v8
	v_cvt_pk_bf16_f32 v17, v17, v18
	v_cvt_pk_bf16_f32 v18, v24, v21
	v_cvt_pk_bf16_f32 v19, v22, v19
	global_store_dwordx4 v[80:81], v[16:19], off offset:256
	v_pk_fma_f32 v[14:15], v[14:15], v[172:173], v[134:135] op_sel_hi:[1,0,1]
	v_max_f32_e32 v9, 0, v9
	v_mul_f32_e32 v16, v8, v8
	v_max_f32_e32 v8, 0, v13
	v_max_f32_e32 v10, 0, v10
	s_mov_b64 s[8:9], 0x140000
	v_max_f32_e32 v12, 0, v12
	v_mul_f32_e32 v8, v8, v8
	v_mul_f32_e32 v13, v9, v9
	v_max_f32_e32 v9, 0, v14
	v_mul_f32_e32 v14, v10, v10
	v_max_f32_e32 v10, 0, v15
	v_max_f32_e32 v11, 0, v11
	v_pk_fma_f32 v[2:3], v[2:3], v[158:159], v[130:131] op_sel_hi:[1,0,1]
	v_pk_fma_f32 v[0:1], v[0:1], v[158:159], v[128:129] op_sel_hi:[1,0,1]
	v_lshl_add_u64 v[72:73], v[120:121], 0, s[8:9]
	v_mul_f32_e32 v12, v12, v12
	v_mul_f32_e32 v9, v9, v9
	v_mul_f32_e32 v10, v10, v10
	v_mul_f32_e32 v11, v11, v11
	v_cvt_pk_bf16_f32 v8, v12, v8
	v_pk_fma_f32 v[6:7], v[6:7], v[158:159], v[134:135] op_sel_hi:[1,0,1]
	v_pk_fma_f32 v[4:5], v[4:5], v[158:159], v[132:133] op_sel_hi:[1,0,1]
	v_max_f32_e32 v0, 0, v0
	v_max_f32_e32 v1, 0, v1
	v_max_f32_e32 v2, 0, v2
	s_mov_b64 s[8:9], 0x160000
	v_cvt_pk_bf16_f32 v9, v9, v10
	v_cvt_pk_bf16_f32 v10, v16, v13
	v_cvt_pk_bf16_f32 v11, v14, v11
	global_store_dwordx4 v[72:73], v[8:11], off offset:256
	v_max_f32_e32 v3, 0, v3
	v_lshl_add_u64 v[56:57], v[120:121], 0, s[8:9]
	v_mul_f32_e32 v8, v0, v0
	v_max_f32_e32 v0, 0, v5
	v_mul_f32_e32 v5, v1, v1
	v_max_f32_e32 v1, 0, v6
	v_mul_f32_e32 v6, v2, v2
	v_max_f32_e32 v2, 0, v7
	v_max_f32_e32 v4, 0, v4
	v_mul_f32_e32 v0, v0, v0
	v_mul_f32_e32 v1, v1, v1
	v_mul_f32_e32 v2, v2, v2
	v_mul_f32_e32 v3, v3, v3
	s_and_b64 vcc, exec, s[2:3]
	s_mov_b64 s[8:9], s[58:59]
	v_mul_f32_e32 v4, v4, v4
	v_cvt_pk_bf16_f32 v0, v4, v0
	v_cvt_pk_bf16_f32 v1, v1, v2
	v_cvt_pk_bf16_f32 v2, v8, v5
	v_cvt_pk_bf16_f32 v3, v6, v3
	global_store_dwordx4 v[56:57], v[0:3], off offset:256
	s_cbranch_vccz .LBB0_343
	s_waitcnt vmcnt(0)
	s_mov_b32 s90, s62
	s_cmpk_gt_u32 s36, 0xff
	s_cbranch_scc1 .LBB0_354
	s_barrier
